# GEMM phases without the per-cluster s_setprio flips (second measure)
# speedup vs baseline: 1.0028x; 1.0028x over previous
.LBB0_342:
	s_and_b64 s[10:11], s[48:49], exec
	s_cselect_b32 s50, s45, s5
	s_cselect_b32 s51, s44, s4
	s_cselect_b32 s53, s47, s9
	s_cselect_b32 s54, s46, s8
	s_add_u32 s55, s8, 0x100
	s_addc_u32 s78, s9, 0
	s_add_u32 s4, s4, 0x40080
	v_mov_b32_e32 v0, 0
	s_addc_u32 s5, s5, 0
	s_mov_b32 s79, -2
	ds_read_b128 v[128:131], v169
	ds_read_b128 v[132:135], v169 offset:1024
	ds_read_b128 v[136:139], v169 offset:2048
	ds_read_b128 v[140:143], v169 offset:3072
	ds_read_b128 v[158:161], v170
	ds_read_b128 v[162:165], v170 offset:1024
	ds_read_b128 v[178:181], v170 offset:2048
	ds_read_b128 v[182:185], v170 offset:3072
	s_add_u32 s8, s4, 0xfffc0080
	s_addc_u32 s9, s5, -1
	s_cmp_eq_u32 s79, 12
	s_cselect_b32 s11, s50, s9
	s_cselect_b32 s10, s51, s8
	s_cselect_b32 s9, s53, s78
	s_cselect_b32 s8, s54, s55
	v_lshl_add_u64 v[218:219], s[4:5], 0, v[156:157]
	s_add_i32 m0, s28, 0xc000
	ds_read_b128 v[186:189], v171
	ds_read_b128 v[190:193], v171 offset:1024
	ds_read_b128 v[194:197], v171 offset:2048
	ds_read_b128 v[198:201], v171 offset:3072
	ds_read_b128 v[202:205], v171 offset:4096
	ds_read_b128 v[206:209], v171 offset:5120
	ds_read_b128 v[210:213], v171 offset:6144
	ds_read_b128 v[214:217], v171 offset:7168
	global_load_lds_dwordx4 v[218:219], off
	v_lshl_add_u64 v[218:219], s[4:5], 0, v[154:155]
	s_add_i32 m0, s28, 0xe000
	s_nop 0
	global_load_lds_dwordx4 v[218:219], off
	s_waitcnt vmcnt(8)
	s_waitcnt lgkmcnt(0)
	s_barrier
	s_waitcnt lgkmcnt(0)
	v_mfma_f32_16x16x32_bf16 v[124:127], v[128:131], v[186:189], 0
	v_mfma_f32_16x16x32_bf16 v[120:123], v[136:139], v[186:189], 0
	v_mfma_f32_16x16x32_bf16 v[108:111], v[128:131], v[194:197], 0
	v_mfma_f32_16x16x32_bf16 v[104:107], v[136:139], v[194:197], 0
	v_mfma_f32_16x16x32_bf16 v[92:95], v[128:131], v[202:205], 0
	v_mfma_f32_16x16x32_bf16 v[88:91], v[136:139], v[202:205], 0
	v_mfma_f32_16x16x32_bf16 v[76:79], v[128:131], v[210:213], 0
	v_mfma_f32_16x16x32_bf16 v[72:75], v[136:139], v[210:213], 0
	v_mfma_f32_16x16x32_bf16 v[124:127], v[132:135], v[190:193], v[124:127]
	v_mfma_f32_16x16x32_bf16 v[120:123], v[140:143], v[190:193], v[120:123]
	v_mfma_f32_16x16x32_bf16 v[108:111], v[132:135], v[198:201], v[108:111]
	v_mfma_f32_16x16x32_bf16 v[104:107], v[140:143], v[198:201], v[104:107]
	v_mfma_f32_16x16x32_bf16 v[92:95], v[132:135], v[206:209], v[92:95]
	v_mfma_f32_16x16x32_bf16 v[88:91], v[140:143], v[206:209], v[88:91]
	v_mfma_f32_16x16x32_bf16 v[76:79], v[132:135], v[214:217], v[76:79]
	v_mfma_f32_16x16x32_bf16 v[72:75], v[140:143], v[214:217], v[72:75]
	v_mfma_f32_16x16x32_bf16 v[116:119], v[158:161], v[186:189], 0
	v_mfma_f32_16x16x32_bf16 v[112:115], v[178:181], v[186:189], 0
	v_mfma_f32_16x16x32_bf16 v[100:103], v[158:161], v[194:197], 0
	v_mfma_f32_16x16x32_bf16 v[96:99], v[178:181], v[194:197], 0
	v_mfma_f32_16x16x32_bf16 v[84:87], v[158:161], v[202:205], 0
	v_mfma_f32_16x16x32_bf16 v[80:83], v[178:181], v[202:205], 0
	v_mfma_f32_16x16x32_bf16 v[68:71], v[158:161], v[210:213], 0
	v_mfma_f32_16x16x32_bf16 v[64:67], v[178:181], v[210:213], 0
	v_mfma_f32_16x16x32_bf16 v[116:119], v[162:165], v[190:193], v[116:119]
	v_mfma_f32_16x16x32_bf16 v[112:115], v[182:185], v[190:193], v[112:115]
	v_mfma_f32_16x16x32_bf16 v[100:103], v[162:165], v[198:201], v[100:103]
	v_mfma_f32_16x16x32_bf16 v[96:99], v[182:185], v[198:201], v[96:99]
	v_mfma_f32_16x16x32_bf16 v[84:87], v[162:165], v[206:209], v[84:87]
	v_mfma_f32_16x16x32_bf16 v[80:83], v[182:185], v[206:209], v[80:83]
	v_mfma_f32_16x16x32_bf16 v[68:71], v[162:165], v[214:217], v[68:71]
	v_mfma_f32_16x16x32_bf16 v[64:67], v[182:185], v[214:217], v[64:67]
	s_barrier
	s_add_i32 s26, s63, s13
	v_lshl_add_u64 v[218:219], s[8:9], 0, v[146:147]
	s_mov_b32 m0, s26
	ds_read_b128 v[186:189], v171 offset:16384
	ds_read_b128 v[190:193], v171 offset:17408
	ds_read_b128 v[194:197], v171 offset:18432
	ds_read_b128 v[198:201], v171 offset:19456
	ds_read_b128 v[202:205], v171 offset:20480
	ds_read_b128 v[206:209], v171 offset:21504
	ds_read_b128 v[210:213], v171 offset:22528
	ds_read_b128 v[214:217], v171 offset:23552
	global_load_lds_dwordx4 v[218:219], off
	s_add_i32 m0, s26, 0x2000
	s_add_u32 s26, s8, 0x40000
	v_lshl_add_u64 v[220:221], s[8:9], 0, v[150:151]
	s_addc_u32 s27, s9, 0
	s_add_i32 s77, s64, s13
	global_load_lds_dwordx4 v[220:221], off
	v_lshl_add_u64 v[222:223], s[26:27], 0, v[146:147]
	s_mov_b32 m0, s77
	v_lshl_add_u64 v[224:225], s[10:11], 0, v[148:149]
	global_load_lds_dwordx4 v[222:223], off
	v_lshl_add_u64 v[222:223], s[26:27], 0, v[150:151]
	s_add_i32 m0, s77, 0x2000
	s_nop 0
	global_load_lds_dwordx4 v[222:223], off
	v_lshl_add_u64 v[222:223], s[10:11], 0, v[144:145]
	s_mov_b32 m0, s28
	s_nop 0
	global_load_lds_dwordx4 v[222:223], off
	s_mov_b32 m0, s29
	s_nop 0
	global_load_lds_dwordx4 v[224:225], off
	s_waitcnt vmcnt(8)
	s_waitcnt lgkmcnt(0)
	s_barrier
	s_waitcnt lgkmcnt(0)
	v_mfma_f32_16x16x32_bf16 v[60:63], v[128:131], v[186:189], 0
	v_mfma_f32_16x16x32_bf16 v[56:59], v[136:139], v[186:189], 0
	v_mfma_f32_16x16x32_bf16 v[44:47], v[128:131], v[194:197], 0
	v_mfma_f32_16x16x32_bf16 v[40:43], v[136:139], v[194:197], 0
	v_mfma_f32_16x16x32_bf16 v[28:31], v[128:131], v[202:205], 0
	v_mfma_f32_16x16x32_bf16 v[24:27], v[136:139], v[202:205], 0
	v_mfma_f32_16x16x32_bf16 v[12:15], v[128:131], v[210:213], 0
	v_mfma_f32_16x16x32_bf16 v[8:11], v[136:139], v[210:213], 0
	v_mfma_f32_16x16x32_bf16 v[60:63], v[132:135], v[190:193], v[60:63]
	v_mfma_f32_16x16x32_bf16 v[56:59], v[140:143], v[190:193], v[56:59]
	v_mfma_f32_16x16x32_bf16 v[44:47], v[132:135], v[198:201], v[44:47]
	v_mfma_f32_16x16x32_bf16 v[40:43], v[140:143], v[198:201], v[40:43]
	v_mfma_f32_16x16x32_bf16 v[28:31], v[132:135], v[206:209], v[28:31]
	v_mfma_f32_16x16x32_bf16 v[24:27], v[140:143], v[206:209], v[24:27]
	v_mfma_f32_16x16x32_bf16 v[12:15], v[132:135], v[214:217], v[12:15]
	v_mfma_f32_16x16x32_bf16 v[8:11], v[140:143], v[214:217], v[8:11]
	v_mfma_f32_16x16x32_bf16 v[52:55], v[158:161], v[186:189], 0
	v_mfma_f32_16x16x32_bf16 v[48:51], v[178:181], v[186:189], 0
	v_mfma_f32_16x16x32_bf16 v[36:39], v[158:161], v[194:197], 0
	v_mfma_f32_16x16x32_bf16 v[32:35], v[178:181], v[194:197], 0
	v_mfma_f32_16x16x32_bf16 v[20:23], v[158:161], v[202:205], 0
	v_mfma_f32_16x16x32_bf16 v[16:19], v[178:181], v[202:205], 0
	v_mfma_f32_16x16x32_bf16 v[4:7], v[158:161], v[210:213], 0
	v_mfma_f32_16x16x32_bf16 v[0:3], v[178:181], v[210:213], 0
	v_mfma_f32_16x16x32_bf16 v[52:55], v[162:165], v[190:193], v[52:55]
	v_mfma_f32_16x16x32_bf16 v[48:51], v[182:185], v[190:193], v[48:51]
	v_mfma_f32_16x16x32_bf16 v[36:39], v[162:165], v[198:201], v[36:39]
	v_mfma_f32_16x16x32_bf16 v[32:35], v[182:185], v[198:201], v[32:35]
	v_mfma_f32_16x16x32_bf16 v[20:23], v[162:165], v[206:209], v[20:23]
	v_mfma_f32_16x16x32_bf16 v[16:19], v[182:185], v[206:209], v[16:19]
	v_mfma_f32_16x16x32_bf16 v[4:7], v[162:165], v[214:217], v[4:7]
	v_mfma_f32_16x16x32_bf16 v[0:3], v[182:185], v[214:217], v[0:3]
	s_barrier
	s_add_i32 s26, 0, 0x18000
	s_add_i32 s27, 0, 0x1c000
	v_add_u32_e32 v140, s26, v168
	v_add_u32_e32 v152, s27, v168
	ds_read_b128 v[128:131], v140
	ds_read_b128 v[132:135], v140 offset:1024
	ds_read_b128 v[136:139], v140 offset:2048
	ds_read_b128 v[140:143], v140 offset:3072
	ds_read_b128 v[158:161], v152
	ds_read_b128 v[162:165], v152 offset:1024
	ds_read_b128 v[178:181], v152 offset:2048
	ds_read_b128 v[182:185], v152 offset:3072
	s_add_u32 s10, s10, 0x40000
	s_addc_u32 s11, s11, 0
	s_mov_b32 m0, s56
	v_lshl_add_u64 v[226:227], s[10:11], 0, v[144:145]
	ds_read_b128 v[186:189], v171 offset:32768
	ds_read_b128 v[190:193], v171 offset:33792
	ds_read_b128 v[194:197], v171 offset:34816
	ds_read_b128 v[198:201], v171 offset:35840
	ds_read_b128 v[202:205], v171 offset:36864
	ds_read_b128 v[206:209], v171 offset:37888
	ds_read_b128 v[210:213], v171 offset:38912
	ds_read_b128 v[214:217], v171 offset:39936
	global_load_lds_dwordx4 v[226:227], off
	v_lshl_add_u64 v[226:227], s[10:11], 0, v[148:149]
	s_mov_b32 m0, s57
	s_nop 0
	global_load_lds_dwordx4 v[226:227], off
	s_waitcnt vmcnt(8)
	s_waitcnt lgkmcnt(0)
	s_barrier
	s_waitcnt lgkmcnt(0)
	v_mfma_f32_16x16x32_bf16 v[124:127], v[128:131], v[186:189], v[124:127]
	v_mfma_f32_16x16x32_bf16 v[120:123], v[136:139], v[186:189], v[120:123]
	v_mfma_f32_16x16x32_bf16 v[108:111], v[128:131], v[194:197], v[108:111]
	v_mfma_f32_16x16x32_bf16 v[104:107], v[136:139], v[194:197], v[104:107]
	v_mfma_f32_16x16x32_bf16 v[92:95], v[128:131], v[202:205], v[92:95]
	v_mfma_f32_16x16x32_bf16 v[88:91], v[136:139], v[202:205], v[88:91]
	v_mfma_f32_16x16x32_bf16 v[76:79], v[128:131], v[210:213], v[76:79]
	v_mfma_f32_16x16x32_bf16 v[72:75], v[136:139], v[210:213], v[72:75]
	v_mfma_f32_16x16x32_bf16 v[124:127], v[132:135], v[190:193], v[124:127]
	v_mfma_f32_16x16x32_bf16 v[120:123], v[140:143], v[190:193], v[120:123]
	v_mfma_f32_16x16x32_bf16 v[108:111], v[132:135], v[198:201], v[108:111]
	v_mfma_f32_16x16x32_bf16 v[104:107], v[140:143], v[198:201], v[104:107]
	v_mfma_f32_16x16x32_bf16 v[92:95], v[132:135], v[206:209], v[92:95]
	v_mfma_f32_16x16x32_bf16 v[88:91], v[140:143], v[206:209], v[88:91]
	v_mfma_f32_16x16x32_bf16 v[76:79], v[132:135], v[214:217], v[76:79]
	v_mfma_f32_16x16x32_bf16 v[72:75], v[140:143], v[214:217], v[72:75]
	v_mfma_f32_16x16x32_bf16 v[116:119], v[158:161], v[186:189], v[116:119]
	v_mfma_f32_16x16x32_bf16 v[112:115], v[178:181], v[186:189], v[112:115]
	v_mfma_f32_16x16x32_bf16 v[100:103], v[158:161], v[194:197], v[100:103]
	v_mfma_f32_16x16x32_bf16 v[96:99], v[178:181], v[194:197], v[96:99]
	v_mfma_f32_16x16x32_bf16 v[84:87], v[158:161], v[202:205], v[84:87]
	v_mfma_f32_16x16x32_bf16 v[80:83], v[178:181], v[202:205], v[80:83]
	v_mfma_f32_16x16x32_bf16 v[68:71], v[158:161], v[210:213], v[68:71]
	v_mfma_f32_16x16x32_bf16 v[64:67], v[178:181], v[210:213], v[64:67]
	v_mfma_f32_16x16x32_bf16 v[116:119], v[162:165], v[190:193], v[116:119]
	v_mfma_f32_16x16x32_bf16 v[112:115], v[182:185], v[190:193], v[112:115]
	v_mfma_f32_16x16x32_bf16 v[100:103], v[162:165], v[198:201], v[100:103]
	v_mfma_f32_16x16x32_bf16 v[96:99], v[182:185], v[198:201], v[96:99]
	v_mfma_f32_16x16x32_bf16 v[84:87], v[162:165], v[206:209], v[84:87]
	v_mfma_f32_16x16x32_bf16 v[80:83], v[182:185], v[206:209], v[80:83]
	v_mfma_f32_16x16x32_bf16 v[68:71], v[162:165], v[214:217], v[68:71]
	v_mfma_f32_16x16x32_bf16 v[64:67], v[182:185], v[214:217], v[64:67]
	s_barrier
	s_add_i32 s10, s26, s13
	v_lshl_add_u64 v[218:219], v[218:219], 0, s[34:35]
	s_mov_b32 m0, s10
	ds_read_b128 v[186:189], v171 offset:49152
	ds_read_b128 v[190:193], v171 offset:50176
	ds_read_b128 v[194:197], v171 offset:51200
	ds_read_b128 v[198:201], v171 offset:52224
	ds_read_b128 v[202:205], v171 offset:53248
	ds_read_b128 v[206:209], v171 offset:54272
	ds_read_b128 v[210:213], v171 offset:55296
	ds_read_b128 v[214:217], v171 offset:56320
	global_load_lds_dwordx4 v[218:219], off
	s_add_i32 m0, s10, 0x2000
	s_add_u32 s8, s8, 0x40080
	v_lshl_add_u64 v[218:219], v[220:221], 0, s[34:35]
	s_addc_u32 s9, s9, 0
	s_add_i32 s10, s27, s13
	global_load_lds_dwordx4 v[218:219], off
	v_lshl_add_u64 v[218:219], s[8:9], 0, v[146:147]
	s_mov_b32 m0, s10
	s_nop 0
	global_load_lds_dwordx4 v[218:219], off
	v_lshl_add_u64 v[218:219], s[8:9], 0, v[150:151]
	s_add_i32 m0, s10, 0x2000
	s_nop 0
	global_load_lds_dwordx4 v[218:219], off
	v_lshl_add_u64 v[218:219], v[222:223], 0, s[34:35]
	s_mov_b32 m0, s61
	s_nop 0
	global_load_lds_dwordx4 v[218:219], off
	v_lshl_add_u64 v[218:219], v[224:225], 0, s[34:35]
	s_mov_b32 m0, s62
	s_nop 0
	global_load_lds_dwordx4 v[218:219], off
	s_waitcnt vmcnt(8)
	s_waitcnt lgkmcnt(0)
	s_barrier
	s_waitcnt lgkmcnt(0)
	v_mfma_f32_16x16x32_bf16 v[60:63], v[128:131], v[186:189], v[60:63]
	v_mfma_f32_16x16x32_bf16 v[56:59], v[136:139], v[186:189], v[56:59]
	v_mfma_f32_16x16x32_bf16 v[44:47], v[128:131], v[194:197], v[44:47]
	v_mfma_f32_16x16x32_bf16 v[40:43], v[136:139], v[194:197], v[40:43]
	v_mfma_f32_16x16x32_bf16 v[28:31], v[128:131], v[202:205], v[28:31]
	v_mfma_f32_16x16x32_bf16 v[24:27], v[136:139], v[202:205], v[24:27]
	v_mfma_f32_16x16x32_bf16 v[12:15], v[128:131], v[210:213], v[12:15]
	v_mfma_f32_16x16x32_bf16 v[8:11], v[136:139], v[210:213], v[8:11]
	v_mfma_f32_16x16x32_bf16 v[60:63], v[132:135], v[190:193], v[60:63]
	v_mfma_f32_16x16x32_bf16 v[56:59], v[140:143], v[190:193], v[56:59]
	v_mfma_f32_16x16x32_bf16 v[44:47], v[132:135], v[198:201], v[44:47]
	v_mfma_f32_16x16x32_bf16 v[40:43], v[140:143], v[198:201], v[40:43]
	v_mfma_f32_16x16x32_bf16 v[28:31], v[132:135], v[206:209], v[28:31]
	v_mfma_f32_16x16x32_bf16 v[24:27], v[140:143], v[206:209], v[24:27]
	v_mfma_f32_16x16x32_bf16 v[12:15], v[132:135], v[214:217], v[12:15]
	v_mfma_f32_16x16x32_bf16 v[8:11], v[140:143], v[214:217], v[8:11]
	v_mfma_f32_16x16x32_bf16 v[52:55], v[158:161], v[186:189], v[52:55]
	v_mfma_f32_16x16x32_bf16 v[48:51], v[178:181], v[186:189], v[48:51]
	v_mfma_f32_16x16x32_bf16 v[36:39], v[158:161], v[194:197], v[36:39]
	v_mfma_f32_16x16x32_bf16 v[32:35], v[178:181], v[194:197], v[32:35]
	v_mfma_f32_16x16x32_bf16 v[20:23], v[158:161], v[202:205], v[20:23]
	v_mfma_f32_16x16x32_bf16 v[16:19], v[178:181], v[202:205], v[16:19]
	v_mfma_f32_16x16x32_bf16 v[4:7], v[158:161], v[210:213], v[4:7]
	v_mfma_f32_16x16x32_bf16 v[0:3], v[178:181], v[210:213], v[0:3]
	v_mfma_f32_16x16x32_bf16 v[52:55], v[162:165], v[190:193], v[52:55]
	v_mfma_f32_16x16x32_bf16 v[48:51], v[182:185], v[190:193], v[48:51]
	v_mfma_f32_16x16x32_bf16 v[36:39], v[162:165], v[198:201], v[36:39]
	v_mfma_f32_16x16x32_bf16 v[32:35], v[182:185], v[198:201], v[32:35]
	v_mfma_f32_16x16x32_bf16 v[20:23], v[162:165], v[206:209], v[20:23]
	v_mfma_f32_16x16x32_bf16 v[16:19], v[182:185], v[206:209], v[16:19]
	v_mfma_f32_16x16x32_bf16 v[4:7], v[162:165], v[214:217], v[4:7]
	v_mfma_f32_16x16x32_bf16 v[0:3], v[182:185], v[214:217], v[0:3]
	s_barrier
	s_add_i32 s79, s79, 2
	s_add_u32 s55, s55, 0x100
	s_addc_u32 s78, s78, 0
	s_add_u32 s4, s4, 0x100
	s_addc_u32 s5, s5, 0
.LBB0_343:
	ds_read_b128 v[128:131], v169
	ds_read_b128 v[132:135], v169 offset:1024
	ds_read_b128 v[136:139], v169 offset:2048
	ds_read_b128 v[140:143], v169 offset:3072
	ds_read_b128 v[158:161], v170
	ds_read_b128 v[162:165], v170 offset:1024
	ds_read_b128 v[178:181], v170 offset:2048
	ds_read_b128 v[182:185], v170 offset:3072
	s_add_u32 s8, s4, 0xfffc0080
	s_addc_u32 s9, s5, -1
	s_cmp_eq_u32 s79, 12
	s_cselect_b32 s11, s50, s9
	s_cselect_b32 s10, s51, s8
	s_cselect_b32 s9, s53, s78
	s_cselect_b32 s8, s54, s55
	v_lshl_add_u64 v[218:219], s[4:5], 0, v[156:157]
	s_add_i32 m0, s28, 0xc000
	ds_read_b128 v[186:189], v171
	ds_read_b128 v[190:193], v171 offset:1024
	ds_read_b128 v[194:197], v171 offset:2048
	ds_read_b128 v[198:201], v171 offset:3072
	ds_read_b128 v[202:205], v171 offset:4096
	ds_read_b128 v[206:209], v171 offset:5120
	ds_read_b128 v[210:213], v171 offset:6144
	ds_read_b128 v[214:217], v171 offset:7168
	global_load_lds_dwordx4 v[218:219], off
	v_lshl_add_u64 v[218:219], s[4:5], 0, v[154:155]
	s_add_i32 m0, s28, 0xe000
	s_nop 0
	global_load_lds_dwordx4 v[218:219], off
	s_waitcnt vmcnt(8)
	s_waitcnt lgkmcnt(0)
	s_barrier
	s_waitcnt lgkmcnt(0)
	v_mfma_f32_16x16x32_bf16 v[124:127], v[128:131], v[186:189], v[124:127]
	v_mfma_f32_16x16x32_bf16 v[120:123], v[136:139], v[186:189], v[120:123]
	v_mfma_f32_16x16x32_bf16 v[108:111], v[128:131], v[194:197], v[108:111]
	v_mfma_f32_16x16x32_bf16 v[104:107], v[136:139], v[194:197], v[104:107]
	v_mfma_f32_16x16x32_bf16 v[92:95], v[128:131], v[202:205], v[92:95]
	v_mfma_f32_16x16x32_bf16 v[88:91], v[136:139], v[202:205], v[88:91]
	v_mfma_f32_16x16x32_bf16 v[76:79], v[128:131], v[210:213], v[76:79]
	v_mfma_f32_16x16x32_bf16 v[72:75], v[136:139], v[210:213], v[72:75]
	v_mfma_f32_16x16x32_bf16 v[124:127], v[132:135], v[190:193], v[124:127]
	v_mfma_f32_16x16x32_bf16 v[120:123], v[140:143], v[190:193], v[120:123]
	v_mfma_f32_16x16x32_bf16 v[108:111], v[132:135], v[198:201], v[108:111]
	v_mfma_f32_16x16x32_bf16 v[104:107], v[140:143], v[198:201], v[104:107]
	v_mfma_f32_16x16x32_bf16 v[92:95], v[132:135], v[206:209], v[92:95]
	v_mfma_f32_16x16x32_bf16 v[88:91], v[140:143], v[206:209], v[88:91]
	v_mfma_f32_16x16x32_bf16 v[76:79], v[132:135], v[214:217], v[76:79]
	v_mfma_f32_16x16x32_bf16 v[72:75], v[140:143], v[214:217], v[72:75]
	v_mfma_f32_16x16x32_bf16 v[116:119], v[158:161], v[186:189], v[116:119]
	v_mfma_f32_16x16x32_bf16 v[112:115], v[178:181], v[186:189], v[112:115]
	v_mfma_f32_16x16x32_bf16 v[100:103], v[158:161], v[194:197], v[100:103]
	v_mfma_f32_16x16x32_bf16 v[96:99], v[178:181], v[194:197], v[96:99]
	v_mfma_f32_16x16x32_bf16 v[84:87], v[158:161], v[202:205], v[84:87]
	v_mfma_f32_16x16x32_bf16 v[80:83], v[178:181], v[202:205], v[80:83]
	v_mfma_f32_16x16x32_bf16 v[68:71], v[158:161], v[210:213], v[68:71]
	v_mfma_f32_16x16x32_bf16 v[64:67], v[178:181], v[210:213], v[64:67]
	v_mfma_f32_16x16x32_bf16 v[116:119], v[162:165], v[190:193], v[116:119]
	v_mfma_f32_16x16x32_bf16 v[112:115], v[182:185], v[190:193], v[112:115]
	v_mfma_f32_16x16x32_bf16 v[100:103], v[162:165], v[198:201], v[100:103]
	v_mfma_f32_16x16x32_bf16 v[96:99], v[182:185], v[198:201], v[96:99]
	v_mfma_f32_16x16x32_bf16 v[84:87], v[162:165], v[206:209], v[84:87]
	v_mfma_f32_16x16x32_bf16 v[80:83], v[182:185], v[206:209], v[80:83]
	v_mfma_f32_16x16x32_bf16 v[68:71], v[162:165], v[214:217], v[68:71]
	v_mfma_f32_16x16x32_bf16 v[64:67], v[182:185], v[214:217], v[64:67]
	s_barrier
	s_add_i32 s26, s63, s13
	v_lshl_add_u64 v[218:219], s[8:9], 0, v[146:147]
	s_mov_b32 m0, s26
	ds_read_b128 v[186:189], v171 offset:16384
	ds_read_b128 v[190:193], v171 offset:17408
	ds_read_b128 v[194:197], v171 offset:18432
	ds_read_b128 v[198:201], v171 offset:19456
	ds_read_b128 v[202:205], v171 offset:20480
	ds_read_b128 v[206:209], v171 offset:21504
	ds_read_b128 v[210:213], v171 offset:22528
	ds_read_b128 v[214:217], v171 offset:23552
	global_load_lds_dwordx4 v[218:219], off
	s_add_i32 m0, s26, 0x2000
	s_add_u32 s26, s8, 0x40000
	v_lshl_add_u64 v[220:221], s[8:9], 0, v[150:151]
	s_addc_u32 s27, s9, 0
	s_add_i32 s77, s64, s13
	global_load_lds_dwordx4 v[220:221], off
	v_lshl_add_u64 v[222:223], s[26:27], 0, v[146:147]
	s_mov_b32 m0, s77
	v_lshl_add_u64 v[224:225], s[10:11], 0, v[148:149]
	global_load_lds_dwordx4 v[222:223], off
	v_lshl_add_u64 v[222:223], s[26:27], 0, v[150:151]
	s_add_i32 m0, s77, 0x2000
	s_nop 0
	global_load_lds_dwordx4 v[222:223], off
	v_lshl_add_u64 v[222:223], s[10:11], 0, v[144:145]
	s_mov_b32 m0, s28
	s_nop 0
	global_load_lds_dwordx4 v[222:223], off
	s_mov_b32 m0, s29
	s_nop 0
	global_load_lds_dwordx4 v[224:225], off
	s_waitcnt vmcnt(8)
	s_waitcnt lgkmcnt(0)
	s_barrier
	s_waitcnt lgkmcnt(0)
	v_mfma_f32_16x16x32_bf16 v[60:63], v[128:131], v[186:189], v[60:63]
	v_mfma_f32_16x16x32_bf16 v[56:59], v[136:139], v[186:189], v[56:59]
	v_mfma_f32_16x16x32_bf16 v[44:47], v[128:131], v[194:197], v[44:47]
	v_mfma_f32_16x16x32_bf16 v[40:43], v[136:139], v[194:197], v[40:43]
	v_mfma_f32_16x16x32_bf16 v[28:31], v[128:131], v[202:205], v[28:31]
	v_mfma_f32_16x16x32_bf16 v[24:27], v[136:139], v[202:205], v[24:27]
	v_mfma_f32_16x16x32_bf16 v[12:15], v[128:131], v[210:213], v[12:15]
	v_mfma_f32_16x16x32_bf16 v[8:11], v[136:139], v[210:213], v[8:11]
	v_mfma_f32_16x16x32_bf16 v[60:63], v[132:135], v[190:193], v[60:63]
	v_mfma_f32_16x16x32_bf16 v[56:59], v[140:143], v[190:193], v[56:59]
	v_mfma_f32_16x16x32_bf16 v[44:47], v[132:135], v[198:201], v[44:47]
	v_mfma_f32_16x16x32_bf16 v[40:43], v[140:143], v[198:201], v[40:43]
	v_mfma_f32_16x16x32_bf16 v[28:31], v[132:135], v[206:209], v[28:31]
	v_mfma_f32_16x16x32_bf16 v[24:27], v[140:143], v[206:209], v[24:27]
	v_mfma_f32_16x16x32_bf16 v[12:15], v[132:135], v[214:217], v[12:15]
	v_mfma_f32_16x16x32_bf16 v[8:11], v[140:143], v[214:217], v[8:11]
	v_mfma_f32_16x16x32_bf16 v[52:55], v[158:161], v[186:189], v[52:55]
	v_mfma_f32_16x16x32_bf16 v[48:51], v[178:181], v[186:189], v[48:51]
	v_mfma_f32_16x16x32_bf16 v[36:39], v[158:161], v[194:197], v[36:39]
	v_mfma_f32_16x16x32_bf16 v[32:35], v[178:181], v[194:197], v[32:35]
	v_mfma_f32_16x16x32_bf16 v[20:23], v[158:161], v[202:205], v[20:23]
	v_mfma_f32_16x16x32_bf16 v[16:19], v[178:181], v[202:205], v[16:19]
	v_mfma_f32_16x16x32_bf16 v[4:7], v[158:161], v[210:213], v[4:7]
	v_mfma_f32_16x16x32_bf16 v[0:3], v[178:181], v[210:213], v[0:3]
	v_mfma_f32_16x16x32_bf16 v[52:55], v[162:165], v[190:193], v[52:55]
	v_mfma_f32_16x16x32_bf16 v[48:51], v[182:185], v[190:193], v[48:51]
	v_mfma_f32_16x16x32_bf16 v[36:39], v[162:165], v[198:201], v[36:39]
	v_mfma_f32_16x16x32_bf16 v[32:35], v[182:185], v[198:201], v[32:35]
	v_mfma_f32_16x16x32_bf16 v[20:23], v[162:165], v[206:209], v[20:23]
	v_mfma_f32_16x16x32_bf16 v[16:19], v[182:185], v[206:209], v[16:19]
	v_mfma_f32_16x16x32_bf16 v[4:7], v[162:165], v[214:217], v[4:7]
	v_mfma_f32_16x16x32_bf16 v[0:3], v[182:185], v[214:217], v[0:3]
	s_barrier
	s_add_i32 s26, 0, 0x18000
	s_add_i32 s27, 0, 0x1c000
	v_add_u32_e32 v140, s26, v168
	v_add_u32_e32 v152, s27, v168
	ds_read_b128 v[128:131], v140
	ds_read_b128 v[132:135], v140 offset:1024
	ds_read_b128 v[136:139], v140 offset:2048
	ds_read_b128 v[140:143], v140 offset:3072
	ds_read_b128 v[158:161], v152
	ds_read_b128 v[162:165], v152 offset:1024
	ds_read_b128 v[178:181], v152 offset:2048
	ds_read_b128 v[182:185], v152 offset:3072
	s_add_u32 s10, s10, 0x40000
	s_addc_u32 s11, s11, 0
	s_mov_b32 m0, s56
	v_lshl_add_u64 v[226:227], s[10:11], 0, v[144:145]
	ds_read_b128 v[186:189], v171 offset:32768
	ds_read_b128 v[190:193], v171 offset:33792
	ds_read_b128 v[194:197], v171 offset:34816
	ds_read_b128 v[198:201], v171 offset:35840
	ds_read_b128 v[202:205], v171 offset:36864
	ds_read_b128 v[206:209], v171 offset:37888
	ds_read_b128 v[210:213], v171 offset:38912
	ds_read_b128 v[214:217], v171 offset:39936
	global_load_lds_dwordx4 v[226:227], off
	v_lshl_add_u64 v[226:227], s[10:11], 0, v[148:149]
	s_mov_b32 m0, s57
	s_nop 0
	global_load_lds_dwordx4 v[226:227], off
	s_waitcnt vmcnt(8)
	s_waitcnt lgkmcnt(0)
	s_barrier
	s_waitcnt lgkmcnt(0)
	v_mfma_f32_16x16x32_bf16 v[124:127], v[128:131], v[186:189], v[124:127]
	v_mfma_f32_16x16x32_bf16 v[120:123], v[136:139], v[186:189], v[120:123]
	v_mfma_f32_16x16x32_bf16 v[108:111], v[128:131], v[194:197], v[108:111]
	v_mfma_f32_16x16x32_bf16 v[104:107], v[136:139], v[194:197], v[104:107]
	v_mfma_f32_16x16x32_bf16 v[92:95], v[128:131], v[202:205], v[92:95]
	v_mfma_f32_16x16x32_bf16 v[88:91], v[136:139], v[202:205], v[88:91]
	v_mfma_f32_16x16x32_bf16 v[76:79], v[128:131], v[210:213], v[76:79]
	v_mfma_f32_16x16x32_bf16 v[72:75], v[136:139], v[210:213], v[72:75]
	v_mfma_f32_16x16x32_bf16 v[124:127], v[132:135], v[190:193], v[124:127]
	v_mfma_f32_16x16x32_bf16 v[120:123], v[140:143], v[190:193], v[120:123]
	v_mfma_f32_16x16x32_bf16 v[108:111], v[132:135], v[198:201], v[108:111]
	v_mfma_f32_16x16x32_bf16 v[104:107], v[140:143], v[198:201], v[104:107]
	v_mfma_f32_16x16x32_bf16 v[92:95], v[132:135], v[206:209], v[92:95]
	v_mfma_f32_16x16x32_bf16 v[88:91], v[140:143], v[206:209], v[88:91]
	v_mfma_f32_16x16x32_bf16 v[76:79], v[132:135], v[214:217], v[76:79]
	v_mfma_f32_16x16x32_bf16 v[72:75], v[140:143], v[214:217], v[72:75]
	v_mfma_f32_16x16x32_bf16 v[116:119], v[158:161], v[186:189], v[116:119]
	v_mfma_f32_16x16x32_bf16 v[112:115], v[178:181], v[186:189], v[112:115]
	v_mfma_f32_16x16x32_bf16 v[100:103], v[158:161], v[194:197], v[100:103]
	v_mfma_f32_16x16x32_bf16 v[96:99], v[178:181], v[194:197], v[96:99]
	v_mfma_f32_16x16x32_bf16 v[84:87], v[158:161], v[202:205], v[84:87]
	v_mfma_f32_16x16x32_bf16 v[80:83], v[178:181], v[202:205], v[80:83]
	v_mfma_f32_16x16x32_bf16 v[68:71], v[158:161], v[210:213], v[68:71]
	v_mfma_f32_16x16x32_bf16 v[64:67], v[178:181], v[210:213], v[64:67]
	v_mfma_f32_16x16x32_bf16 v[116:119], v[162:165], v[190:193], v[116:119]
	v_mfma_f32_16x16x32_bf16 v[112:115], v[182:185], v[190:193], v[112:115]
	v_mfma_f32_16x16x32_bf16 v[100:103], v[162:165], v[198:201], v[100:103]
	v_mfma_f32_16x16x32_bf16 v[96:99], v[182:185], v[198:201], v[96:99]
	v_mfma_f32_16x16x32_bf16 v[84:87], v[162:165], v[206:209], v[84:87]
	v_mfma_f32_16x16x32_bf16 v[80:83], v[182:185], v[206:209], v[80:83]
	v_mfma_f32_16x16x32_bf16 v[68:71], v[162:165], v[214:217], v[68:71]
	v_mfma_f32_16x16x32_bf16 v[64:67], v[182:185], v[214:217], v[64:67]
	s_barrier
	s_add_i32 s10, s26, s13
	v_lshl_add_u64 v[218:219], v[218:219], 0, s[34:35]
	s_mov_b32 m0, s10
	ds_read_b128 v[186:189], v171 offset:49152
	ds_read_b128 v[190:193], v171 offset:50176
	ds_read_b128 v[194:197], v171 offset:51200
	ds_read_b128 v[198:201], v171 offset:52224
	ds_read_b128 v[202:205], v171 offset:53248
	ds_read_b128 v[206:209], v171 offset:54272
	ds_read_b128 v[210:213], v171 offset:55296
	ds_read_b128 v[214:217], v171 offset:56320
	global_load_lds_dwordx4 v[218:219], off
	s_add_i32 m0, s10, 0x2000
	s_add_u32 s8, s8, 0x40080
	v_lshl_add_u64 v[218:219], v[220:221], 0, s[34:35]
	s_addc_u32 s9, s9, 0
	s_add_i32 s10, s27, s13
	global_load_lds_dwordx4 v[218:219], off
	v_lshl_add_u64 v[218:219], s[8:9], 0, v[146:147]
	s_mov_b32 m0, s10
	s_nop 0
	global_load_lds_dwordx4 v[218:219], off
	v_lshl_add_u64 v[218:219], s[8:9], 0, v[150:151]
	s_add_i32 m0, s10, 0x2000
	s_nop 0
	global_load_lds_dwordx4 v[218:219], off
	v_lshl_add_u64 v[218:219], v[222:223], 0, s[34:35]
	s_mov_b32 m0, s61
	s_nop 0
	global_load_lds_dwordx4 v[218:219], off
	v_lshl_add_u64 v[218:219], v[224:225], 0, s[34:35]
	s_mov_b32 m0, s62
	s_nop 0
	global_load_lds_dwordx4 v[218:219], off
	s_waitcnt vmcnt(8)
	s_waitcnt lgkmcnt(0)
	s_barrier
	s_waitcnt lgkmcnt(0)
	v_mfma_f32_16x16x32_bf16 v[60:63], v[128:131], v[186:189], v[60:63]
	v_mfma_f32_16x16x32_bf16 v[56:59], v[136:139], v[186:189], v[56:59]
	v_mfma_f32_16x16x32_bf16 v[44:47], v[128:131], v[194:197], v[44:47]
	v_mfma_f32_16x16x32_bf16 v[40:43], v[136:139], v[194:197], v[40:43]
	v_mfma_f32_16x16x32_bf16 v[28:31], v[128:131], v[202:205], v[28:31]
	v_mfma_f32_16x16x32_bf16 v[24:27], v[136:139], v[202:205], v[24:27]
	v_mfma_f32_16x16x32_bf16 v[12:15], v[128:131], v[210:213], v[12:15]
	v_mfma_f32_16x16x32_bf16 v[8:11], v[136:139], v[210:213], v[8:11]
	v_mfma_f32_16x16x32_bf16 v[60:63], v[132:135], v[190:193], v[60:63]
	v_mfma_f32_16x16x32_bf16 v[56:59], v[140:143], v[190:193], v[56:59]
	v_mfma_f32_16x16x32_bf16 v[44:47], v[132:135], v[198:201], v[44:47]
	v_mfma_f32_16x16x32_bf16 v[40:43], v[140:143], v[198:201], v[40:43]
	v_mfma_f32_16x16x32_bf16 v[28:31], v[132:135], v[206:209], v[28:31]
	v_mfma_f32_16x16x32_bf16 v[24:27], v[140:143], v[206:209], v[24:27]
	v_mfma_f32_16x16x32_bf16 v[12:15], v[132:135], v[214:217], v[12:15]
	v_mfma_f32_16x16x32_bf16 v[8:11], v[140:143], v[214:217], v[8:11]
	v_mfma_f32_16x16x32_bf16 v[52:55], v[158:161], v[186:189], v[52:55]
	v_mfma_f32_16x16x32_bf16 v[48:51], v[178:181], v[186:189], v[48:51]
	v_mfma_f32_16x16x32_bf16 v[36:39], v[158:161], v[194:197], v[36:39]
	v_mfma_f32_16x16x32_bf16 v[32:35], v[178:181], v[194:197], v[32:35]
	v_mfma_f32_16x16x32_bf16 v[20:23], v[158:161], v[202:205], v[20:23]
	v_mfma_f32_16x16x32_bf16 v[16:19], v[178:181], v[202:205], v[16:19]
	v_mfma_f32_16x16x32_bf16 v[4:7], v[158:161], v[210:213], v[4:7]
	v_mfma_f32_16x16x32_bf16 v[0:3], v[178:181], v[210:213], v[0:3]
	v_mfma_f32_16x16x32_bf16 v[52:55], v[162:165], v[190:193], v[52:55]
	v_mfma_f32_16x16x32_bf16 v[48:51], v[182:185], v[190:193], v[48:51]
	v_mfma_f32_16x16x32_bf16 v[36:39], v[162:165], v[198:201], v[36:39]
	v_mfma_f32_16x16x32_bf16 v[32:35], v[182:185], v[198:201], v[32:35]
	v_mfma_f32_16x16x32_bf16 v[20:23], v[162:165], v[206:209], v[20:23]
	v_mfma_f32_16x16x32_bf16 v[16:19], v[182:185], v[206:209], v[16:19]
	v_mfma_f32_16x16x32_bf16 v[4:7], v[162:165], v[214:217], v[4:7]
	v_mfma_f32_16x16x32_bf16 v[0:3], v[182:185], v[214:217], v[0:3]
	s_barrier
	s_add_i32 s79, s79, 2
	s_add_u32 s55, s55, 0x100
	s_addc_u32 s78, s78, 0
	s_add_u32 s4, s4, 0x100
	s_addc_u32 s5, s5, 0
	s_cmp_gt_u32 s79, 13
	s_cbranch_scc0 .LBB0_343
	s_and_b64 vcc, exec, s[18:19]
	s_cbranch_vccz .LBB0_346
	s_barrier

.LBB0_818:
	s_add_u32 s5, s70, 0x100
	s_addc_u32 s61, s71, 0
	s_add_u32 s68, s68, 0x40080
	v_mov_b32_e32 v0, 0
	s_addc_u32 s69, s69, 0
	s_mov_b32 s91, -2
	s_waitcnt lgkmcnt(0)
	ds_read_b128 v[104:107], v229
	ds_read_b128 v[108:111], v229 offset:1024
	ds_read_b128 v[128:131], v229 offset:2048
	ds_read_b128 v[132:135], v229 offset:3072
	ds_read_b128 v[144:147], v230
	ds_read_b128 v[148:151], v230 offset:1024
	ds_read_b128 v[152:155], v230 offset:2048
	ds_read_b128 v[156:159], v230 offset:3072
	s_add_u32 s26, s68, 0xfffc0080
	s_addc_u32 s27, s69, -1
	s_cmp_eq_u32 s91, 12
	s_cselect_b32 s73, s63, s27
	s_cselect_b32 s72, s62, s26
	s_cselect_b32 s71, s65, s61
	s_cselect_b32 s70, s64, s5
	v_lshl_add_u64 v[204:205], s[68:69], 0, v[202:203]
	s_add_i32 m0, s28, 0xc000
	ds_read_b128 v[160:163], v231
	ds_read_b128 v[164:167], v231 offset:1024
	ds_read_b128 v[168:171], v231 offset:2048
	ds_read_b128 v[172:175], v231 offset:3072
	ds_read_b128 v[176:179], v231 offset:4096
	ds_read_b128 v[180:183], v231 offset:5120
	ds_read_b128 v[184:187], v231 offset:6144
	ds_read_b128 v[188:191], v231 offset:7168
	global_load_lds_dwordx4 v[204:205], off
	v_lshl_add_u64 v[204:205], s[68:69], 0, v[200:201]
	s_add_i32 m0, s28, 0xe000
	s_nop 0
	global_load_lds_dwordx4 v[204:205], off
	s_waitcnt vmcnt(8)
	s_waitcnt lgkmcnt(0)
	s_barrier
	s_waitcnt lgkmcnt(0)
	v_mfma_f32_16x16x32_bf16 v[140:143], v[104:107], v[160:163], 0
	v_mfma_f32_16x16x32_bf16 v[136:139], v[128:131], v[160:163], 0
	v_mfma_f32_16x16x32_bf16 v[116:119], v[104:107], v[168:171], 0
	v_mfma_f32_16x16x32_bf16 v[112:115], v[128:131], v[168:171], 0
	v_mfma_f32_16x16x32_bf16 v[92:95], v[104:107], v[176:179], 0
	v_mfma_f32_16x16x32_bf16 v[88:91], v[128:131], v[176:179], 0
	v_mfma_f32_16x16x32_bf16 v[76:79], v[104:107], v[184:187], 0
	v_mfma_f32_16x16x32_bf16 v[72:75], v[128:131], v[184:187], 0
	v_mfma_f32_16x16x32_bf16 v[140:143], v[108:111], v[164:167], v[140:143]
	v_mfma_f32_16x16x32_bf16 v[136:139], v[132:135], v[164:167], v[136:139]
	v_mfma_f32_16x16x32_bf16 v[116:119], v[108:111], v[172:175], v[116:119]
	v_mfma_f32_16x16x32_bf16 v[112:115], v[132:135], v[172:175], v[112:115]
	v_mfma_f32_16x16x32_bf16 v[92:95], v[108:111], v[180:183], v[92:95]
	v_mfma_f32_16x16x32_bf16 v[88:91], v[132:135], v[180:183], v[88:91]
	v_mfma_f32_16x16x32_bf16 v[76:79], v[108:111], v[188:191], v[76:79]
	v_mfma_f32_16x16x32_bf16 v[72:75], v[132:135], v[188:191], v[72:75]
	v_mfma_f32_16x16x32_bf16 v[124:127], v[144:147], v[160:163], 0
	v_mfma_f32_16x16x32_bf16 v[120:123], v[152:155], v[160:163], 0
	v_mfma_f32_16x16x32_bf16 v[100:103], v[144:147], v[168:171], 0
	v_mfma_f32_16x16x32_bf16 v[96:99], v[152:155], v[168:171], 0
	v_mfma_f32_16x16x32_bf16 v[84:87], v[144:147], v[176:179], 0
	v_mfma_f32_16x16x32_bf16 v[80:83], v[152:155], v[176:179], 0
	v_mfma_f32_16x16x32_bf16 v[68:71], v[144:147], v[184:187], 0
	v_mfma_f32_16x16x32_bf16 v[64:67], v[152:155], v[184:187], 0
	v_mfma_f32_16x16x32_bf16 v[124:127], v[148:151], v[164:167], v[124:127]
	v_mfma_f32_16x16x32_bf16 v[120:123], v[156:159], v[164:167], v[120:123]
	v_mfma_f32_16x16x32_bf16 v[100:103], v[148:151], v[172:175], v[100:103]
	v_mfma_f32_16x16x32_bf16 v[96:99], v[156:159], v[172:175], v[96:99]
	v_mfma_f32_16x16x32_bf16 v[84:87], v[148:151], v[180:183], v[84:87]
	v_mfma_f32_16x16x32_bf16 v[80:83], v[156:159], v[180:183], v[80:83]
	v_mfma_f32_16x16x32_bf16 v[68:71], v[148:151], v[188:191], v[68:71]
	v_mfma_f32_16x16x32_bf16 v[64:67], v[156:159], v[188:191], v[64:67]
	s_barrier
	s_add_i32 s26, s83, s3
	v_lshl_add_u64 v[204:205], s[70:71], 0, v[194:195]
	s_mov_b32 m0, s26
	ds_read_b128 v[160:163], v231 offset:16384
	ds_read_b128 v[164:167], v231 offset:17408
	ds_read_b128 v[168:171], v231 offset:18432
	ds_read_b128 v[172:175], v231 offset:19456
	ds_read_b128 v[176:179], v231 offset:20480
	ds_read_b128 v[180:183], v231 offset:21504
	ds_read_b128 v[184:187], v231 offset:22528
	ds_read_b128 v[188:191], v231 offset:23552
	global_load_lds_dwordx4 v[204:205], off
	s_add_i32 m0, s26, 0x2000
	s_add_u32 s26, s70, 0x40000
	v_lshl_add_u64 v[206:207], s[70:71], 0, v[198:199]
	s_addc_u32 s27, s71, 0
	s_add_i32 s77, s84, s3
	global_load_lds_dwordx4 v[206:207], off
	v_lshl_add_u64 v[208:209], s[26:27], 0, v[194:195]
	s_mov_b32 m0, s77
	v_lshl_add_u64 v[210:211], s[72:73], 0, v[196:197]
	global_load_lds_dwordx4 v[208:209], off
	v_lshl_add_u64 v[208:209], s[26:27], 0, v[198:199]
	s_add_i32 m0, s77, 0x2000
	s_nop 0
	global_load_lds_dwordx4 v[208:209], off
	v_lshl_add_u64 v[208:209], s[72:73], 0, v[192:193]
	s_mov_b32 m0, s28
	s_nop 0
	global_load_lds_dwordx4 v[208:209], off
	s_mov_b32 m0, s29
	s_nop 0
	global_load_lds_dwordx4 v[210:211], off
	s_waitcnt vmcnt(8)
	s_waitcnt lgkmcnt(0)
	s_barrier
	s_waitcnt lgkmcnt(0)
	v_mfma_f32_16x16x32_bf16 v[60:63], v[104:107], v[160:163], 0
	v_mfma_f32_16x16x32_bf16 v[56:59], v[128:131], v[160:163], 0
	v_mfma_f32_16x16x32_bf16 v[44:47], v[104:107], v[168:171], 0
	v_mfma_f32_16x16x32_bf16 v[40:43], v[128:131], v[168:171], 0
	v_mfma_f32_16x16x32_bf16 v[28:31], v[104:107], v[176:179], 0
	v_mfma_f32_16x16x32_bf16 v[24:27], v[128:131], v[176:179], 0
	v_mfma_f32_16x16x32_bf16 v[12:15], v[104:107], v[184:187], 0
	v_mfma_f32_16x16x32_bf16 v[8:11], v[128:131], v[184:187], 0
	v_mfma_f32_16x16x32_bf16 v[60:63], v[108:111], v[164:167], v[60:63]
	v_mfma_f32_16x16x32_bf16 v[56:59], v[132:135], v[164:167], v[56:59]
	v_mfma_f32_16x16x32_bf16 v[44:47], v[108:111], v[172:175], v[44:47]
	v_mfma_f32_16x16x32_bf16 v[40:43], v[132:135], v[172:175], v[40:43]
	v_mfma_f32_16x16x32_bf16 v[28:31], v[108:111], v[180:183], v[28:31]
	v_mfma_f32_16x16x32_bf16 v[24:27], v[132:135], v[180:183], v[24:27]
	v_mfma_f32_16x16x32_bf16 v[12:15], v[108:111], v[188:191], v[12:15]
	v_mfma_f32_16x16x32_bf16 v[8:11], v[132:135], v[188:191], v[8:11]
	v_mfma_f32_16x16x32_bf16 v[52:55], v[144:147], v[160:163], 0
	v_mfma_f32_16x16x32_bf16 v[48:51], v[152:155], v[160:163], 0
	v_mfma_f32_16x16x32_bf16 v[36:39], v[144:147], v[168:171], 0
	v_mfma_f32_16x16x32_bf16 v[32:35], v[152:155], v[168:171], 0
	v_mfma_f32_16x16x32_bf16 v[20:23], v[144:147], v[176:179], 0
	v_mfma_f32_16x16x32_bf16 v[16:19], v[152:155], v[176:179], 0
	v_mfma_f32_16x16x32_bf16 v[4:7], v[144:147], v[184:187], 0
	v_mfma_f32_16x16x32_bf16 v[0:3], v[152:155], v[184:187], 0
	v_mfma_f32_16x16x32_bf16 v[52:55], v[148:151], v[164:167], v[52:55]
	v_mfma_f32_16x16x32_bf16 v[48:51], v[156:159], v[164:167], v[48:51]
	v_mfma_f32_16x16x32_bf16 v[36:39], v[148:151], v[172:175], v[36:39]
	v_mfma_f32_16x16x32_bf16 v[32:35], v[156:159], v[172:175], v[32:35]
	v_mfma_f32_16x16x32_bf16 v[20:23], v[148:151], v[180:183], v[20:23]
	v_mfma_f32_16x16x32_bf16 v[16:19], v[156:159], v[180:183], v[16:19]
	v_mfma_f32_16x16x32_bf16 v[4:7], v[148:151], v[188:191], v[4:7]
	v_mfma_f32_16x16x32_bf16 v[0:3], v[156:159], v[188:191], v[0:3]
	s_barrier
	s_add_i32 s77, 0, 0x18000
	s_add_i32 s92, 0, 0x1c000
	v_add_u32_e32 v132, s77, v228
	v_add_u32_e32 v156, s92, v228
	ds_read_b128 v[104:107], v132
	ds_read_b128 v[108:111], v132 offset:1024
	ds_read_b128 v[128:131], v132 offset:2048
	ds_read_b128 v[132:135], v132 offset:3072
	ds_read_b128 v[144:147], v156
	ds_read_b128 v[148:151], v156 offset:1024
	ds_read_b128 v[152:155], v156 offset:2048
	ds_read_b128 v[156:159], v156 offset:3072
	s_add_u32 s26, s72, 0x40000
	s_addc_u32 s27, s73, 0
	s_mov_b32 m0, s30
	v_lshl_add_u64 v[212:213], s[26:27], 0, v[192:193]
	ds_read_b128 v[160:163], v231 offset:32768
	ds_read_b128 v[164:167], v231 offset:33792
	ds_read_b128 v[168:171], v231 offset:34816
	ds_read_b128 v[172:175], v231 offset:35840
	ds_read_b128 v[176:179], v231 offset:36864
	ds_read_b128 v[180:183], v231 offset:37888
	ds_read_b128 v[184:187], v231 offset:38912
	ds_read_b128 v[188:191], v231 offset:39936
	global_load_lds_dwordx4 v[212:213], off
	v_lshl_add_u64 v[212:213], s[26:27], 0, v[196:197]
	s_mov_b32 m0, s31
	s_nop 0
	global_load_lds_dwordx4 v[212:213], off
	s_waitcnt vmcnt(8)
	s_waitcnt lgkmcnt(0)
	s_barrier
	s_waitcnt lgkmcnt(0)
	v_mfma_f32_16x16x32_bf16 v[140:143], v[104:107], v[160:163], v[140:143]
	v_mfma_f32_16x16x32_bf16 v[136:139], v[128:131], v[160:163], v[136:139]
	v_mfma_f32_16x16x32_bf16 v[116:119], v[104:107], v[168:171], v[116:119]
	v_mfma_f32_16x16x32_bf16 v[112:115], v[128:131], v[168:171], v[112:115]
	v_mfma_f32_16x16x32_bf16 v[92:95], v[104:107], v[176:179], v[92:95]
	v_mfma_f32_16x16x32_bf16 v[88:91], v[128:131], v[176:179], v[88:91]
	v_mfma_f32_16x16x32_bf16 v[76:79], v[104:107], v[184:187], v[76:79]
	v_mfma_f32_16x16x32_bf16 v[72:75], v[128:131], v[184:187], v[72:75]
	v_mfma_f32_16x16x32_bf16 v[140:143], v[108:111], v[164:167], v[140:143]
	v_mfma_f32_16x16x32_bf16 v[136:139], v[132:135], v[164:167], v[136:139]
	v_mfma_f32_16x16x32_bf16 v[116:119], v[108:111], v[172:175], v[116:119]
	v_mfma_f32_16x16x32_bf16 v[112:115], v[132:135], v[172:175], v[112:115]
	v_mfma_f32_16x16x32_bf16 v[92:95], v[108:111], v[180:183], v[92:95]
	v_mfma_f32_16x16x32_bf16 v[88:91], v[132:135], v[180:183], v[88:91]
	v_mfma_f32_16x16x32_bf16 v[76:79], v[108:111], v[188:191], v[76:79]
	v_mfma_f32_16x16x32_bf16 v[72:75], v[132:135], v[188:191], v[72:75]
	v_mfma_f32_16x16x32_bf16 v[124:127], v[144:147], v[160:163], v[124:127]
	v_mfma_f32_16x16x32_bf16 v[120:123], v[152:155], v[160:163], v[120:123]
	v_mfma_f32_16x16x32_bf16 v[100:103], v[144:147], v[168:171], v[100:103]
	v_mfma_f32_16x16x32_bf16 v[96:99], v[152:155], v[168:171], v[96:99]
	v_mfma_f32_16x16x32_bf16 v[84:87], v[144:147], v[176:179], v[84:87]
	v_mfma_f32_16x16x32_bf16 v[80:83], v[152:155], v[176:179], v[80:83]
	v_mfma_f32_16x16x32_bf16 v[68:71], v[144:147], v[184:187], v[68:71]
	v_mfma_f32_16x16x32_bf16 v[64:67], v[152:155], v[184:187], v[64:67]
	v_mfma_f32_16x16x32_bf16 v[124:127], v[148:151], v[164:167], v[124:127]
	v_mfma_f32_16x16x32_bf16 v[120:123], v[156:159], v[164:167], v[120:123]
	v_mfma_f32_16x16x32_bf16 v[100:103], v[148:151], v[172:175], v[100:103]
	v_mfma_f32_16x16x32_bf16 v[96:99], v[156:159], v[172:175], v[96:99]
	v_mfma_f32_16x16x32_bf16 v[84:87], v[148:151], v[180:183], v[84:87]
	v_mfma_f32_16x16x32_bf16 v[80:83], v[156:159], v[180:183], v[80:83]
	v_mfma_f32_16x16x32_bf16 v[68:71], v[148:151], v[188:191], v[68:71]
	v_mfma_f32_16x16x32_bf16 v[64:67], v[156:159], v[188:191], v[64:67]
	s_barrier
	s_add_i32 s26, s77, s3
	v_lshl_add_u64 v[204:205], v[204:205], 0, s[10:11]
	s_mov_b32 m0, s26
	ds_read_b128 v[160:163], v231 offset:49152
	ds_read_b128 v[164:167], v231 offset:50176
	ds_read_b128 v[168:171], v231 offset:51200
	ds_read_b128 v[172:175], v231 offset:52224
	ds_read_b128 v[176:179], v231 offset:53248
	ds_read_b128 v[180:183], v231 offset:54272
	ds_read_b128 v[184:187], v231 offset:55296
	ds_read_b128 v[188:191], v231 offset:56320
	global_load_lds_dwordx4 v[204:205], off
	s_add_i32 m0, s26, 0x2000
	s_add_u32 s26, s70, 0x40080
	v_lshl_add_u64 v[204:205], v[206:207], 0, s[10:11]
	s_addc_u32 s27, s71, 0
	s_add_i32 s70, s92, s3
	global_load_lds_dwordx4 v[204:205], off
	v_lshl_add_u64 v[204:205], s[26:27], 0, v[194:195]
	s_mov_b32 m0, s70
	s_nop 0
	global_load_lds_dwordx4 v[204:205], off
	v_lshl_add_u64 v[204:205], s[26:27], 0, v[198:199]
	s_add_i32 m0, s70, 0x2000
	s_nop 0
	global_load_lds_dwordx4 v[204:205], off
	v_lshl_add_u64 v[204:205], v[208:209], 0, s[10:11]
	s_mov_b32 m0, s81
	s_nop 0
	global_load_lds_dwordx4 v[204:205], off
	v_lshl_add_u64 v[204:205], v[210:211], 0, s[10:11]
	s_mov_b32 m0, s82
	s_nop 0
	global_load_lds_dwordx4 v[204:205], off
	s_waitcnt vmcnt(8)
	s_waitcnt lgkmcnt(0)
	s_barrier
	s_waitcnt lgkmcnt(0)
	v_mfma_f32_16x16x32_bf16 v[60:63], v[104:107], v[160:163], v[60:63]
	v_mfma_f32_16x16x32_bf16 v[56:59], v[128:131], v[160:163], v[56:59]
	v_mfma_f32_16x16x32_bf16 v[44:47], v[104:107], v[168:171], v[44:47]
	v_mfma_f32_16x16x32_bf16 v[40:43], v[128:131], v[168:171], v[40:43]
	v_mfma_f32_16x16x32_bf16 v[28:31], v[104:107], v[176:179], v[28:31]
	v_mfma_f32_16x16x32_bf16 v[24:27], v[128:131], v[176:179], v[24:27]
	v_mfma_f32_16x16x32_bf16 v[12:15], v[104:107], v[184:187], v[12:15]
	v_mfma_f32_16x16x32_bf16 v[8:11], v[128:131], v[184:187], v[8:11]
	v_mfma_f32_16x16x32_bf16 v[60:63], v[108:111], v[164:167], v[60:63]
	v_mfma_f32_16x16x32_bf16 v[56:59], v[132:135], v[164:167], v[56:59]
	v_mfma_f32_16x16x32_bf16 v[44:47], v[108:111], v[172:175], v[44:47]
	v_mfma_f32_16x16x32_bf16 v[40:43], v[132:135], v[172:175], v[40:43]
	v_mfma_f32_16x16x32_bf16 v[28:31], v[108:111], v[180:183], v[28:31]
	v_mfma_f32_16x16x32_bf16 v[24:27], v[132:135], v[180:183], v[24:27]
	v_mfma_f32_16x16x32_bf16 v[12:15], v[108:111], v[188:191], v[12:15]
	v_mfma_f32_16x16x32_bf16 v[8:11], v[132:135], v[188:191], v[8:11]
	v_mfma_f32_16x16x32_bf16 v[52:55], v[144:147], v[160:163], v[52:55]
	v_mfma_f32_16x16x32_bf16 v[48:51], v[152:155], v[160:163], v[48:51]
	v_mfma_f32_16x16x32_bf16 v[36:39], v[144:147], v[168:171], v[36:39]
	v_mfma_f32_16x16x32_bf16 v[32:35], v[152:155], v[168:171], v[32:35]
	v_mfma_f32_16x16x32_bf16 v[20:23], v[144:147], v[176:179], v[20:23]
	v_mfma_f32_16x16x32_bf16 v[16:19], v[152:155], v[176:179], v[16:19]
	v_mfma_f32_16x16x32_bf16 v[4:7], v[144:147], v[184:187], v[4:7]
	v_mfma_f32_16x16x32_bf16 v[0:3], v[152:155], v[184:187], v[0:3]
	v_mfma_f32_16x16x32_bf16 v[52:55], v[148:151], v[164:167], v[52:55]
	v_mfma_f32_16x16x32_bf16 v[48:51], v[156:159], v[164:167], v[48:51]
	v_mfma_f32_16x16x32_bf16 v[36:39], v[148:151], v[172:175], v[36:39]
	v_mfma_f32_16x16x32_bf16 v[32:35], v[156:159], v[172:175], v[32:35]
	v_mfma_f32_16x16x32_bf16 v[20:23], v[148:151], v[180:183], v[20:23]
	v_mfma_f32_16x16x32_bf16 v[16:19], v[156:159], v[180:183], v[16:19]
	v_mfma_f32_16x16x32_bf16 v[4:7], v[148:151], v[188:191], v[4:7]
	v_mfma_f32_16x16x32_bf16 v[0:3], v[156:159], v[188:191], v[0:3]
	s_barrier
	s_add_i32 s91, s91, 2
	s_add_u32 s5, s5, 0x100
	s_addc_u32 s61, s61, 0
	s_add_u32 s68, s68, 0x100
	s_addc_u32 s69, s69, 0
.LBB0_819:
	ds_read_b128 v[104:107], v229
	ds_read_b128 v[108:111], v229 offset:1024
	ds_read_b128 v[128:131], v229 offset:2048
	ds_read_b128 v[132:135], v229 offset:3072
	ds_read_b128 v[144:147], v230
	ds_read_b128 v[148:151], v230 offset:1024
	ds_read_b128 v[152:155], v230 offset:2048
	ds_read_b128 v[156:159], v230 offset:3072
	s_add_u32 s26, s68, 0xfffc0080
	s_addc_u32 s27, s69, -1
	s_cmp_eq_u32 s91, 12
	s_cselect_b32 s73, s63, s27
	s_cselect_b32 s72, s62, s26
	s_cselect_b32 s71, s65, s61
	s_cselect_b32 s70, s64, s5
	v_lshl_add_u64 v[204:205], s[68:69], 0, v[202:203]
	s_add_i32 m0, s28, 0xc000
	ds_read_b128 v[160:163], v231
	ds_read_b128 v[164:167], v231 offset:1024
	ds_read_b128 v[168:171], v231 offset:2048
	ds_read_b128 v[172:175], v231 offset:3072
	ds_read_b128 v[176:179], v231 offset:4096
	ds_read_b128 v[180:183], v231 offset:5120
	ds_read_b128 v[184:187], v231 offset:6144
	ds_read_b128 v[188:191], v231 offset:7168
	global_load_lds_dwordx4 v[204:205], off
	v_lshl_add_u64 v[204:205], s[68:69], 0, v[200:201]
	s_add_i32 m0, s28, 0xe000
	s_nop 0
	global_load_lds_dwordx4 v[204:205], off
	s_waitcnt vmcnt(8)
	s_waitcnt lgkmcnt(0)
	s_barrier
	s_waitcnt lgkmcnt(0)
	v_mfma_f32_16x16x32_bf16 v[140:143], v[104:107], v[160:163], v[140:143]
	v_mfma_f32_16x16x32_bf16 v[136:139], v[128:131], v[160:163], v[136:139]
	v_mfma_f32_16x16x32_bf16 v[116:119], v[104:107], v[168:171], v[116:119]
	v_mfma_f32_16x16x32_bf16 v[112:115], v[128:131], v[168:171], v[112:115]
	v_mfma_f32_16x16x32_bf16 v[92:95], v[104:107], v[176:179], v[92:95]
	v_mfma_f32_16x16x32_bf16 v[88:91], v[128:131], v[176:179], v[88:91]
	v_mfma_f32_16x16x32_bf16 v[76:79], v[104:107], v[184:187], v[76:79]
	v_mfma_f32_16x16x32_bf16 v[72:75], v[128:131], v[184:187], v[72:75]
	v_mfma_f32_16x16x32_bf16 v[140:143], v[108:111], v[164:167], v[140:143]
	v_mfma_f32_16x16x32_bf16 v[136:139], v[132:135], v[164:167], v[136:139]
	v_mfma_f32_16x16x32_bf16 v[116:119], v[108:111], v[172:175], v[116:119]
	v_mfma_f32_16x16x32_bf16 v[112:115], v[132:135], v[172:175], v[112:115]
	v_mfma_f32_16x16x32_bf16 v[92:95], v[108:111], v[180:183], v[92:95]
	v_mfma_f32_16x16x32_bf16 v[88:91], v[132:135], v[180:183], v[88:91]
	v_mfma_f32_16x16x32_bf16 v[76:79], v[108:111], v[188:191], v[76:79]
	v_mfma_f32_16x16x32_bf16 v[72:75], v[132:135], v[188:191], v[72:75]
	v_mfma_f32_16x16x32_bf16 v[124:127], v[144:147], v[160:163], v[124:127]
	v_mfma_f32_16x16x32_bf16 v[120:123], v[152:155], v[160:163], v[120:123]
	v_mfma_f32_16x16x32_bf16 v[100:103], v[144:147], v[168:171], v[100:103]
	v_mfma_f32_16x16x32_bf16 v[96:99], v[152:155], v[168:171], v[96:99]
	v_mfma_f32_16x16x32_bf16 v[84:87], v[144:147], v[176:179], v[84:87]
	v_mfma_f32_16x16x32_bf16 v[80:83], v[152:155], v[176:179], v[80:83]
	v_mfma_f32_16x16x32_bf16 v[68:71], v[144:147], v[184:187], v[68:71]
	v_mfma_f32_16x16x32_bf16 v[64:67], v[152:155], v[184:187], v[64:67]
	v_mfma_f32_16x16x32_bf16 v[124:127], v[148:151], v[164:167], v[124:127]
	v_mfma_f32_16x16x32_bf16 v[120:123], v[156:159], v[164:167], v[120:123]
	v_mfma_f32_16x16x32_bf16 v[100:103], v[148:151], v[172:175], v[100:103]
	v_mfma_f32_16x16x32_bf16 v[96:99], v[156:159], v[172:175], v[96:99]
	v_mfma_f32_16x16x32_bf16 v[84:87], v[148:151], v[180:183], v[84:87]
	v_mfma_f32_16x16x32_bf16 v[80:83], v[156:159], v[180:183], v[80:83]
	v_mfma_f32_16x16x32_bf16 v[68:71], v[148:151], v[188:191], v[68:71]
	v_mfma_f32_16x16x32_bf16 v[64:67], v[156:159], v[188:191], v[64:67]
	s_barrier
	s_add_i32 s26, s83, s3
	v_lshl_add_u64 v[204:205], s[70:71], 0, v[194:195]
	s_mov_b32 m0, s26
	ds_read_b128 v[160:163], v231 offset:16384
	ds_read_b128 v[164:167], v231 offset:17408
	ds_read_b128 v[168:171], v231 offset:18432
	ds_read_b128 v[172:175], v231 offset:19456
	ds_read_b128 v[176:179], v231 offset:20480
	ds_read_b128 v[180:183], v231 offset:21504
	ds_read_b128 v[184:187], v231 offset:22528
	ds_read_b128 v[188:191], v231 offset:23552
	global_load_lds_dwordx4 v[204:205], off
	s_add_i32 m0, s26, 0x2000
	s_add_u32 s26, s70, 0x40000
	v_lshl_add_u64 v[206:207], s[70:71], 0, v[198:199]
	s_addc_u32 s27, s71, 0
	s_add_i32 s77, s84, s3
	global_load_lds_dwordx4 v[206:207], off
	v_lshl_add_u64 v[208:209], s[26:27], 0, v[194:195]
	s_mov_b32 m0, s77
	v_lshl_add_u64 v[210:211], s[72:73], 0, v[196:197]
	global_load_lds_dwordx4 v[208:209], off
	v_lshl_add_u64 v[208:209], s[26:27], 0, v[198:199]
	s_add_i32 m0, s77, 0x2000
	s_nop 0
	global_load_lds_dwordx4 v[208:209], off
	v_lshl_add_u64 v[208:209], s[72:73], 0, v[192:193]
	s_mov_b32 m0, s28
	s_nop 0
	global_load_lds_dwordx4 v[208:209], off
	s_mov_b32 m0, s29
	s_nop 0
	global_load_lds_dwordx4 v[210:211], off
	s_waitcnt vmcnt(8)
	s_waitcnt lgkmcnt(0)
	s_barrier
	s_waitcnt lgkmcnt(0)
	v_mfma_f32_16x16x32_bf16 v[60:63], v[104:107], v[160:163], v[60:63]
	v_mfma_f32_16x16x32_bf16 v[56:59], v[128:131], v[160:163], v[56:59]
	v_mfma_f32_16x16x32_bf16 v[44:47], v[104:107], v[168:171], v[44:47]
	v_mfma_f32_16x16x32_bf16 v[40:43], v[128:131], v[168:171], v[40:43]
	v_mfma_f32_16x16x32_bf16 v[28:31], v[104:107], v[176:179], v[28:31]
	v_mfma_f32_16x16x32_bf16 v[24:27], v[128:131], v[176:179], v[24:27]
	v_mfma_f32_16x16x32_bf16 v[12:15], v[104:107], v[184:187], v[12:15]
	v_mfma_f32_16x16x32_bf16 v[8:11], v[128:131], v[184:187], v[8:11]
	v_mfma_f32_16x16x32_bf16 v[60:63], v[108:111], v[164:167], v[60:63]
	v_mfma_f32_16x16x32_bf16 v[56:59], v[132:135], v[164:167], v[56:59]
	v_mfma_f32_16x16x32_bf16 v[44:47], v[108:111], v[172:175], v[44:47]
	v_mfma_f32_16x16x32_bf16 v[40:43], v[132:135], v[172:175], v[40:43]
	v_mfma_f32_16x16x32_bf16 v[28:31], v[108:111], v[180:183], v[28:31]
	v_mfma_f32_16x16x32_bf16 v[24:27], v[132:135], v[180:183], v[24:27]
	v_mfma_f32_16x16x32_bf16 v[12:15], v[108:111], v[188:191], v[12:15]
	v_mfma_f32_16x16x32_bf16 v[8:11], v[132:135], v[188:191], v[8:11]
	v_mfma_f32_16x16x32_bf16 v[52:55], v[144:147], v[160:163], v[52:55]
	v_mfma_f32_16x16x32_bf16 v[48:51], v[152:155], v[160:163], v[48:51]
	v_mfma_f32_16x16x32_bf16 v[36:39], v[144:147], v[168:171], v[36:39]
	v_mfma_f32_16x16x32_bf16 v[32:35], v[152:155], v[168:171], v[32:35]
	v_mfma_f32_16x16x32_bf16 v[20:23], v[144:147], v[176:179], v[20:23]
	v_mfma_f32_16x16x32_bf16 v[16:19], v[152:155], v[176:179], v[16:19]
	v_mfma_f32_16x16x32_bf16 v[4:7], v[144:147], v[184:187], v[4:7]
	v_mfma_f32_16x16x32_bf16 v[0:3], v[152:155], v[184:187], v[0:3]
	v_mfma_f32_16x16x32_bf16 v[52:55], v[148:151], v[164:167], v[52:55]
	v_mfma_f32_16x16x32_bf16 v[48:51], v[156:159], v[164:167], v[48:51]
	v_mfma_f32_16x16x32_bf16 v[36:39], v[148:151], v[172:175], v[36:39]
	v_mfma_f32_16x16x32_bf16 v[32:35], v[156:159], v[172:175], v[32:35]
	v_mfma_f32_16x16x32_bf16 v[20:23], v[148:151], v[180:183], v[20:23]
	v_mfma_f32_16x16x32_bf16 v[16:19], v[156:159], v[180:183], v[16:19]
	v_mfma_f32_16x16x32_bf16 v[4:7], v[148:151], v[188:191], v[4:7]
	v_mfma_f32_16x16x32_bf16 v[0:3], v[156:159], v[188:191], v[0:3]
	s_barrier
	s_add_i32 s77, 0, 0x18000
	s_add_i32 s92, 0, 0x1c000
	v_add_u32_e32 v132, s77, v228
	v_add_u32_e32 v156, s92, v228
	ds_read_b128 v[104:107], v132
	ds_read_b128 v[108:111], v132 offset:1024
	ds_read_b128 v[128:131], v132 offset:2048
	ds_read_b128 v[132:135], v132 offset:3072
	ds_read_b128 v[144:147], v156
	ds_read_b128 v[148:151], v156 offset:1024
	ds_read_b128 v[152:155], v156 offset:2048
	ds_read_b128 v[156:159], v156 offset:3072
	s_add_u32 s26, s72, 0x40000
	s_addc_u32 s27, s73, 0
	s_mov_b32 m0, s30
	v_lshl_add_u64 v[212:213], s[26:27], 0, v[192:193]
	ds_read_b128 v[160:163], v231 offset:32768
	ds_read_b128 v[164:167], v231 offset:33792
	ds_read_b128 v[168:171], v231 offset:34816
	ds_read_b128 v[172:175], v231 offset:35840
	ds_read_b128 v[176:179], v231 offset:36864
	ds_read_b128 v[180:183], v231 offset:37888
	ds_read_b128 v[184:187], v231 offset:38912
	ds_read_b128 v[188:191], v231 offset:39936
	global_load_lds_dwordx4 v[212:213], off
	v_lshl_add_u64 v[212:213], s[26:27], 0, v[196:197]
	s_mov_b32 m0, s31
	s_nop 0
	global_load_lds_dwordx4 v[212:213], off
	s_waitcnt vmcnt(8)
	s_waitcnt lgkmcnt(0)
	s_barrier
	s_waitcnt lgkmcnt(0)
	v_mfma_f32_16x16x32_bf16 v[140:143], v[104:107], v[160:163], v[140:143]
	v_mfma_f32_16x16x32_bf16 v[136:139], v[128:131], v[160:163], v[136:139]
	v_mfma_f32_16x16x32_bf16 v[116:119], v[104:107], v[168:171], v[116:119]
	v_mfma_f32_16x16x32_bf16 v[112:115], v[128:131], v[168:171], v[112:115]
	v_mfma_f32_16x16x32_bf16 v[92:95], v[104:107], v[176:179], v[92:95]
	v_mfma_f32_16x16x32_bf16 v[88:91], v[128:131], v[176:179], v[88:91]
	v_mfma_f32_16x16x32_bf16 v[76:79], v[104:107], v[184:187], v[76:79]
	v_mfma_f32_16x16x32_bf16 v[72:75], v[128:131], v[184:187], v[72:75]
	v_mfma_f32_16x16x32_bf16 v[140:143], v[108:111], v[164:167], v[140:143]
	v_mfma_f32_16x16x32_bf16 v[136:139], v[132:135], v[164:167], v[136:139]
	v_mfma_f32_16x16x32_bf16 v[116:119], v[108:111], v[172:175], v[116:119]
	v_mfma_f32_16x16x32_bf16 v[112:115], v[132:135], v[172:175], v[112:115]
	v_mfma_f32_16x16x32_bf16 v[92:95], v[108:111], v[180:183], v[92:95]
	v_mfma_f32_16x16x32_bf16 v[88:91], v[132:135], v[180:183], v[88:91]
	v_mfma_f32_16x16x32_bf16 v[76:79], v[108:111], v[188:191], v[76:79]
	v_mfma_f32_16x16x32_bf16 v[72:75], v[132:135], v[188:191], v[72:75]
	v_mfma_f32_16x16x32_bf16 v[124:127], v[144:147], v[160:163], v[124:127]
	v_mfma_f32_16x16x32_bf16 v[120:123], v[152:155], v[160:163], v[120:123]
	v_mfma_f32_16x16x32_bf16 v[100:103], v[144:147], v[168:171], v[100:103]
	v_mfma_f32_16x16x32_bf16 v[96:99], v[152:155], v[168:171], v[96:99]
	v_mfma_f32_16x16x32_bf16 v[84:87], v[144:147], v[176:179], v[84:87]
	v_mfma_f32_16x16x32_bf16 v[80:83], v[152:155], v[176:179], v[80:83]
	v_mfma_f32_16x16x32_bf16 v[68:71], v[144:147], v[184:187], v[68:71]
	v_mfma_f32_16x16x32_bf16 v[64:67], v[152:155], v[184:187], v[64:67]
	v_mfma_f32_16x16x32_bf16 v[124:127], v[148:151], v[164:167], v[124:127]
	v_mfma_f32_16x16x32_bf16 v[120:123], v[156:159], v[164:167], v[120:123]
	v_mfma_f32_16x16x32_bf16 v[100:103], v[148:151], v[172:175], v[100:103]
	v_mfma_f32_16x16x32_bf16 v[96:99], v[156:159], v[172:175], v[96:99]
	v_mfma_f32_16x16x32_bf16 v[84:87], v[148:151], v[180:183], v[84:87]
	v_mfma_f32_16x16x32_bf16 v[80:83], v[156:159], v[180:183], v[80:83]
	v_mfma_f32_16x16x32_bf16 v[68:71], v[148:151], v[188:191], v[68:71]
	v_mfma_f32_16x16x32_bf16 v[64:67], v[156:159], v[188:191], v[64:67]
	s_barrier
	s_add_i32 s26, s77, s3
	v_lshl_add_u64 v[204:205], v[204:205], 0, s[10:11]
	s_mov_b32 m0, s26
	ds_read_b128 v[160:163], v231 offset:49152
	ds_read_b128 v[164:167], v231 offset:50176
	ds_read_b128 v[168:171], v231 offset:51200
	ds_read_b128 v[172:175], v231 offset:52224
	ds_read_b128 v[176:179], v231 offset:53248
	ds_read_b128 v[180:183], v231 offset:54272
	ds_read_b128 v[184:187], v231 offset:55296
	ds_read_b128 v[188:191], v231 offset:56320
	global_load_lds_dwordx4 v[204:205], off
	s_add_i32 m0, s26, 0x2000
	s_add_u32 s26, s70, 0x40080
	v_lshl_add_u64 v[204:205], v[206:207], 0, s[10:11]
	s_addc_u32 s27, s71, 0
	s_add_i32 s70, s92, s3
	global_load_lds_dwordx4 v[204:205], off
	v_lshl_add_u64 v[204:205], s[26:27], 0, v[194:195]
	s_mov_b32 m0, s70
	s_nop 0
	global_load_lds_dwordx4 v[204:205], off
	v_lshl_add_u64 v[204:205], s[26:27], 0, v[198:199]
	s_add_i32 m0, s70, 0x2000
	s_nop 0
	global_load_lds_dwordx4 v[204:205], off
	v_lshl_add_u64 v[204:205], v[208:209], 0, s[10:11]
	s_mov_b32 m0, s81
	s_nop 0
	global_load_lds_dwordx4 v[204:205], off
	v_lshl_add_u64 v[204:205], v[210:211], 0, s[10:11]
	s_mov_b32 m0, s82
	s_nop 0
	global_load_lds_dwordx4 v[204:205], off
	s_waitcnt vmcnt(8)
	s_waitcnt lgkmcnt(0)
	s_barrier
	s_waitcnt lgkmcnt(0)
	v_mfma_f32_16x16x32_bf16 v[60:63], v[104:107], v[160:163], v[60:63]
	v_mfma_f32_16x16x32_bf16 v[56:59], v[128:131], v[160:163], v[56:59]
	v_mfma_f32_16x16x32_bf16 v[44:47], v[104:107], v[168:171], v[44:47]
	v_mfma_f32_16x16x32_bf16 v[40:43], v[128:131], v[168:171], v[40:43]
	v_mfma_f32_16x16x32_bf16 v[28:31], v[104:107], v[176:179], v[28:31]
	v_mfma_f32_16x16x32_bf16 v[24:27], v[128:131], v[176:179], v[24:27]
	v_mfma_f32_16x16x32_bf16 v[12:15], v[104:107], v[184:187], v[12:15]
	v_mfma_f32_16x16x32_bf16 v[8:11], v[128:131], v[184:187], v[8:11]
	v_mfma_f32_16x16x32_bf16 v[60:63], v[108:111], v[164:167], v[60:63]
	v_mfma_f32_16x16x32_bf16 v[56:59], v[132:135], v[164:167], v[56:59]
	v_mfma_f32_16x16x32_bf16 v[44:47], v[108:111], v[172:175], v[44:47]
	v_mfma_f32_16x16x32_bf16 v[40:43], v[132:135], v[172:175], v[40:43]
	v_mfma_f32_16x16x32_bf16 v[28:31], v[108:111], v[180:183], v[28:31]
	v_mfma_f32_16x16x32_bf16 v[24:27], v[132:135], v[180:183], v[24:27]
	v_mfma_f32_16x16x32_bf16 v[12:15], v[108:111], v[188:191], v[12:15]
	v_mfma_f32_16x16x32_bf16 v[8:11], v[132:135], v[188:191], v[8:11]
	v_mfma_f32_16x16x32_bf16 v[52:55], v[144:147], v[160:163], v[52:55]
	v_mfma_f32_16x16x32_bf16 v[48:51], v[152:155], v[160:163], v[48:51]
	v_mfma_f32_16x16x32_bf16 v[36:39], v[144:147], v[168:171], v[36:39]
	v_mfma_f32_16x16x32_bf16 v[32:35], v[152:155], v[168:171], v[32:35]
	v_mfma_f32_16x16x32_bf16 v[20:23], v[144:147], v[176:179], v[20:23]
	v_mfma_f32_16x16x32_bf16 v[16:19], v[152:155], v[176:179], v[16:19]
	v_mfma_f32_16x16x32_bf16 v[4:7], v[144:147], v[184:187], v[4:7]
	v_mfma_f32_16x16x32_bf16 v[0:3], v[152:155], v[184:187], v[0:3]
	v_mfma_f32_16x16x32_bf16 v[52:55], v[148:151], v[164:167], v[52:55]
	v_mfma_f32_16x16x32_bf16 v[48:51], v[156:159], v[164:167], v[48:51]
	v_mfma_f32_16x16x32_bf16 v[36:39], v[148:151], v[172:175], v[36:39]
	v_mfma_f32_16x16x32_bf16 v[32:35], v[156:159], v[172:175], v[32:35]
	v_mfma_f32_16x16x32_bf16 v[20:23], v[148:151], v[180:183], v[20:23]
	v_mfma_f32_16x16x32_bf16 v[16:19], v[156:159], v[180:183], v[16:19]
	v_mfma_f32_16x16x32_bf16 v[4:7], v[148:151], v[188:191], v[4:7]
	v_mfma_f32_16x16x32_bf16 v[0:3], v[156:159], v[188:191], v[0:3]
	s_barrier
	s_add_i32 s91, s91, 2
	s_add_u32 s5, s5, 0x100
	s_addc_u32 s61, s61, 0
	s_add_u32 s68, s68, 0x100
	s_addc_u32 s69, s69, 0
	s_cmp_gt_u32 s91, 13
	s_cbranch_scc0 .LBB0_819
	s_and_b64 vcc, exec, s[8:9]
	s_cbranch_vccz .LBB0_822
	s_barrier

.LBB0_952:
	s_add_u32 s7, s10, 0x100
	s_addc_u32 s31, s11, 0
	s_add_u32 s8, s8, 0x40080
	v_mov_b32_e32 v2, 0
	s_addc_u32 s9, s9, 0
	s_mov_b32 s51, -2
	ds_read_b128 v[130:133], v167
	ds_read_b128 v[134:137], v167 offset:1024
	ds_read_b128 v[138:141], v167 offset:2048
	ds_read_b128 v[142:145], v167 offset:3072
	ds_read_b128 v[160:163], v168
	ds_read_b128 v[172:175], v168 offset:1024
	ds_read_b128 v[176:179], v168 offset:2048
	ds_read_b128 v[180:183], v168 offset:3072
	s_add_u32 s10, s8, 0xfffc0080
	s_addc_u32 s11, s9, -1
	s_cmp_eq_u32 s51, 12
	s_cselect_b32 s59, s53, s11
	s_cselect_b32 s58, s52, s10
	s_cselect_b32 s11, s57, s31
	s_cselect_b32 s10, s56, s7
	v_lshl_add_u64 v[164:165], s[8:9], 0, v[158:159]
	s_add_i32 m0, s84, 0xc000
	ds_read_b128 v[184:187], v169
	ds_read_b128 v[188:191], v169 offset:1024
	ds_read_b128 v[192:195], v169 offset:2048
	ds_read_b128 v[196:199], v169 offset:3072
	ds_read_b128 v[200:203], v169 offset:4096
	ds_read_b128 v[204:207], v169 offset:5120
	ds_read_b128 v[208:211], v169 offset:6144
	ds_read_b128 v[212:215], v169 offset:7168
	global_load_lds_dwordx4 v[164:165], off
	v_lshl_add_u64 v[164:165], s[8:9], 0, v[156:157]
	s_add_i32 m0, s84, 0xe000
	s_nop 0
	global_load_lds_dwordx4 v[164:165], off
	s_waitcnt vmcnt(8)
	s_waitcnt lgkmcnt(0)
	s_barrier
	s_waitcnt lgkmcnt(0)
	v_mfma_f32_16x16x32_bf16 v[126:129], v[130:133], v[184:187], 0
	v_mfma_f32_16x16x32_bf16 v[122:125], v[138:141], v[184:187], 0
	v_mfma_f32_16x16x32_bf16 v[110:113], v[130:133], v[192:195], 0
	v_mfma_f32_16x16x32_bf16 v[106:109], v[138:141], v[192:195], 0
	v_mfma_f32_16x16x32_bf16 v[94:97], v[130:133], v[200:203], 0
	v_mfma_f32_16x16x32_bf16 v[90:93], v[138:141], v[200:203], 0
	v_mfma_f32_16x16x32_bf16 v[78:81], v[130:133], v[208:211], 0
	v_mfma_f32_16x16x32_bf16 v[74:77], v[138:141], v[208:211], 0
	v_mfma_f32_16x16x32_bf16 v[126:129], v[134:137], v[188:191], v[126:129]
	v_mfma_f32_16x16x32_bf16 v[122:125], v[142:145], v[188:191], v[122:125]
	v_mfma_f32_16x16x32_bf16 v[110:113], v[134:137], v[196:199], v[110:113]
	v_mfma_f32_16x16x32_bf16 v[106:109], v[142:145], v[196:199], v[106:109]
	v_mfma_f32_16x16x32_bf16 v[94:97], v[134:137], v[204:207], v[94:97]
	v_mfma_f32_16x16x32_bf16 v[90:93], v[142:145], v[204:207], v[90:93]
	v_mfma_f32_16x16x32_bf16 v[78:81], v[134:137], v[212:215], v[78:81]
	v_mfma_f32_16x16x32_bf16 v[74:77], v[142:145], v[212:215], v[74:77]
	v_mfma_f32_16x16x32_bf16 v[118:121], v[160:163], v[184:187], 0
	v_mfma_f32_16x16x32_bf16 v[114:117], v[176:179], v[184:187], 0
	v_mfma_f32_16x16x32_bf16 v[102:105], v[160:163], v[192:195], 0
	v_mfma_f32_16x16x32_bf16 v[98:101], v[176:179], v[192:195], 0
	v_mfma_f32_16x16x32_bf16 v[86:89], v[160:163], v[200:203], 0
	v_mfma_f32_16x16x32_bf16 v[82:85], v[176:179], v[200:203], 0
	v_mfma_f32_16x16x32_bf16 v[70:73], v[160:163], v[208:211], 0
	v_mfma_f32_16x16x32_bf16 v[66:69], v[176:179], v[208:211], 0
	v_mfma_f32_16x16x32_bf16 v[118:121], v[172:175], v[188:191], v[118:121]
	v_mfma_f32_16x16x32_bf16 v[114:117], v[180:183], v[188:191], v[114:117]
	v_mfma_f32_16x16x32_bf16 v[102:105], v[172:175], v[196:199], v[102:105]
	v_mfma_f32_16x16x32_bf16 v[98:101], v[180:183], v[196:199], v[98:101]
	v_mfma_f32_16x16x32_bf16 v[86:89], v[172:175], v[204:207], v[86:89]
	v_mfma_f32_16x16x32_bf16 v[82:85], v[180:183], v[204:207], v[82:85]
	v_mfma_f32_16x16x32_bf16 v[70:73], v[172:175], v[212:215], v[70:73]
	v_mfma_f32_16x16x32_bf16 v[66:69], v[180:183], v[212:215], v[66:69]
	s_barrier
	s_add_i32 s26, s94, s39
	v_lshl_add_u64 v[164:165], s[10:11], 0, v[148:149]
	s_mov_b32 m0, s26
	ds_read_b128 v[184:187], v169 offset:16384
	ds_read_b128 v[188:191], v169 offset:17408
	ds_read_b128 v[192:195], v169 offset:18432
	ds_read_b128 v[196:199], v169 offset:19456
	ds_read_b128 v[200:203], v169 offset:20480
	ds_read_b128 v[204:207], v169 offset:21504
	ds_read_b128 v[208:211], v169 offset:22528
	ds_read_b128 v[212:215], v169 offset:23552
	global_load_lds_dwordx4 v[164:165], off
	s_add_i32 m0, s26, 0x2000
	s_add_u32 s26, s10, 0x40000
	v_lshl_add_u64 v[216:217], s[10:11], 0, v[152:153]
	s_addc_u32 s27, s11, 0
	s_add_i32 s60, s95, s39
	global_load_lds_dwordx4 v[216:217], off
	v_lshl_add_u64 v[218:219], s[26:27], 0, v[148:149]
	s_mov_b32 m0, s60
	v_lshl_add_u64 v[220:221], s[58:59], 0, v[150:151]
	global_load_lds_dwordx4 v[218:219], off
	v_lshl_add_u64 v[218:219], s[26:27], 0, v[152:153]
	s_add_i32 m0, s60, 0x2000
	s_nop 0
	global_load_lds_dwordx4 v[218:219], off
	v_lshl_add_u64 v[218:219], s[58:59], 0, v[146:147]
	s_mov_b32 m0, s84
	s_nop 0
	global_load_lds_dwordx4 v[218:219], off
	s_mov_b32 m0, s85
	s_nop 0
	global_load_lds_dwordx4 v[220:221], off
	s_waitcnt vmcnt(8)
	s_waitcnt lgkmcnt(0)
	s_barrier
	s_waitcnt lgkmcnt(0)
	v_mfma_f32_16x16x32_bf16 v[62:65], v[130:133], v[184:187], 0
	v_mfma_f32_16x16x32_bf16 v[58:61], v[138:141], v[184:187], 0
	v_mfma_f32_16x16x32_bf16 v[46:49], v[130:133], v[192:195], 0
	v_mfma_f32_16x16x32_bf16 v[42:45], v[138:141], v[192:195], 0
	v_mfma_f32_16x16x32_bf16 v[30:33], v[130:133], v[200:203], 0
	v_mfma_f32_16x16x32_bf16 v[26:29], v[138:141], v[200:203], 0
	v_mfma_f32_16x16x32_bf16 v[14:17], v[130:133], v[208:211], 0
	v_mfma_f32_16x16x32_bf16 v[10:13], v[138:141], v[208:211], 0
	v_mfma_f32_16x16x32_bf16 v[62:65], v[134:137], v[188:191], v[62:65]
	v_mfma_f32_16x16x32_bf16 v[58:61], v[142:145], v[188:191], v[58:61]
	v_mfma_f32_16x16x32_bf16 v[46:49], v[134:137], v[196:199], v[46:49]
	v_mfma_f32_16x16x32_bf16 v[42:45], v[142:145], v[196:199], v[42:45]
	v_mfma_f32_16x16x32_bf16 v[30:33], v[134:137], v[204:207], v[30:33]
	v_mfma_f32_16x16x32_bf16 v[26:29], v[142:145], v[204:207], v[26:29]
	v_mfma_f32_16x16x32_bf16 v[14:17], v[134:137], v[212:215], v[14:17]
	v_mfma_f32_16x16x32_bf16 v[10:13], v[142:145], v[212:215], v[10:13]
	v_mfma_f32_16x16x32_bf16 v[54:57], v[160:163], v[184:187], 0
	v_mfma_f32_16x16x32_bf16 v[50:53], v[176:179], v[184:187], 0
	v_mfma_f32_16x16x32_bf16 v[38:41], v[160:163], v[192:195], 0
	v_mfma_f32_16x16x32_bf16 v[34:37], v[176:179], v[192:195], 0
	v_mfma_f32_16x16x32_bf16 v[22:25], v[160:163], v[200:203], 0
	v_mfma_f32_16x16x32_bf16 v[18:21], v[176:179], v[200:203], 0
	v_mfma_f32_16x16x32_bf16 v[6:9], v[160:163], v[208:211], 0
	v_mfma_f32_16x16x32_bf16 v[2:5], v[176:179], v[208:211], 0
	v_mfma_f32_16x16x32_bf16 v[54:57], v[172:175], v[188:191], v[54:57]
	v_mfma_f32_16x16x32_bf16 v[50:53], v[180:183], v[188:191], v[50:53]
	v_mfma_f32_16x16x32_bf16 v[38:41], v[172:175], v[196:199], v[38:41]
	v_mfma_f32_16x16x32_bf16 v[34:37], v[180:183], v[196:199], v[34:37]
	v_mfma_f32_16x16x32_bf16 v[22:25], v[172:175], v[204:207], v[22:25]
	v_mfma_f32_16x16x32_bf16 v[18:21], v[180:183], v[204:207], v[18:21]
	v_mfma_f32_16x16x32_bf16 v[6:9], v[172:175], v[212:215], v[6:9]
	v_mfma_f32_16x16x32_bf16 v[2:5], v[180:183], v[212:215], v[2:5]
	s_barrier
	s_add_i32 s60, 0, 0x18000
	v_add_u32_e32 v1, s60, v166
	s_add_i32 s61, 0, 0x1c000
	ds_read_b128 v[130:133], v1
	ds_read_b128 v[134:137], v1 offset:1024
	ds_read_b128 v[138:141], v1 offset:2048
	ds_read_b128 v[142:145], v1 offset:3072
	v_add_u32_e32 v1, s61, v166
	ds_read_b128 v[160:163], v1
	ds_read_b128 v[172:175], v1 offset:1024
	ds_read_b128 v[176:179], v1 offset:2048
	ds_read_b128 v[180:183], v1 offset:3072
	s_add_u32 s26, s58, 0x40000
	s_addc_u32 s27, s59, 0
	s_mov_b32 m0, s86
	v_lshl_add_u64 v[222:223], s[26:27], 0, v[146:147]
	ds_read_b128 v[184:187], v169 offset:32768
	ds_read_b128 v[188:191], v169 offset:33792
	ds_read_b128 v[192:195], v169 offset:34816
	ds_read_b128 v[196:199], v169 offset:35840
	ds_read_b128 v[200:203], v169 offset:36864
	ds_read_b128 v[204:207], v169 offset:37888
	ds_read_b128 v[208:211], v169 offset:38912
	ds_read_b128 v[212:215], v169 offset:39936
	global_load_lds_dwordx4 v[222:223], off
	v_lshl_add_u64 v[222:223], s[26:27], 0, v[150:151]
	s_mov_b32 m0, s87
	s_nop 0
	global_load_lds_dwordx4 v[222:223], off
	s_waitcnt vmcnt(8)
	s_waitcnt lgkmcnt(0)
	s_barrier
	s_waitcnt lgkmcnt(0)
	v_mfma_f32_16x16x32_bf16 v[126:129], v[130:133], v[184:187], v[126:129]
	v_mfma_f32_16x16x32_bf16 v[122:125], v[138:141], v[184:187], v[122:125]
	v_mfma_f32_16x16x32_bf16 v[110:113], v[130:133], v[192:195], v[110:113]
	v_mfma_f32_16x16x32_bf16 v[106:109], v[138:141], v[192:195], v[106:109]
	v_mfma_f32_16x16x32_bf16 v[94:97], v[130:133], v[200:203], v[94:97]
	v_mfma_f32_16x16x32_bf16 v[90:93], v[138:141], v[200:203], v[90:93]
	v_mfma_f32_16x16x32_bf16 v[78:81], v[130:133], v[208:211], v[78:81]
	v_mfma_f32_16x16x32_bf16 v[74:77], v[138:141], v[208:211], v[74:77]
	v_mfma_f32_16x16x32_bf16 v[126:129], v[134:137], v[188:191], v[126:129]
	v_mfma_f32_16x16x32_bf16 v[122:125], v[142:145], v[188:191], v[122:125]
	v_mfma_f32_16x16x32_bf16 v[110:113], v[134:137], v[196:199], v[110:113]
	v_mfma_f32_16x16x32_bf16 v[106:109], v[142:145], v[196:199], v[106:109]
	v_mfma_f32_16x16x32_bf16 v[94:97], v[134:137], v[204:207], v[94:97]
	v_mfma_f32_16x16x32_bf16 v[90:93], v[142:145], v[204:207], v[90:93]
	v_mfma_f32_16x16x32_bf16 v[78:81], v[134:137], v[212:215], v[78:81]
	v_mfma_f32_16x16x32_bf16 v[74:77], v[142:145], v[212:215], v[74:77]
	v_mfma_f32_16x16x32_bf16 v[118:121], v[160:163], v[184:187], v[118:121]
	v_mfma_f32_16x16x32_bf16 v[114:117], v[176:179], v[184:187], v[114:117]
	v_mfma_f32_16x16x32_bf16 v[102:105], v[160:163], v[192:195], v[102:105]
	v_mfma_f32_16x16x32_bf16 v[98:101], v[176:179], v[192:195], v[98:101]
	v_mfma_f32_16x16x32_bf16 v[86:89], v[160:163], v[200:203], v[86:89]
	v_mfma_f32_16x16x32_bf16 v[82:85], v[176:179], v[200:203], v[82:85]
	v_mfma_f32_16x16x32_bf16 v[70:73], v[160:163], v[208:211], v[70:73]
	v_mfma_f32_16x16x32_bf16 v[66:69], v[176:179], v[208:211], v[66:69]
	v_mfma_f32_16x16x32_bf16 v[118:121], v[172:175], v[188:191], v[118:121]
	v_mfma_f32_16x16x32_bf16 v[114:117], v[180:183], v[188:191], v[114:117]
	v_mfma_f32_16x16x32_bf16 v[102:105], v[172:175], v[196:199], v[102:105]
	v_mfma_f32_16x16x32_bf16 v[98:101], v[180:183], v[196:199], v[98:101]
	v_mfma_f32_16x16x32_bf16 v[86:89], v[172:175], v[204:207], v[86:89]
	v_mfma_f32_16x16x32_bf16 v[82:85], v[180:183], v[204:207], v[82:85]
	v_mfma_f32_16x16x32_bf16 v[70:73], v[172:175], v[212:215], v[70:73]
	v_mfma_f32_16x16x32_bf16 v[66:69], v[180:183], v[212:215], v[66:69]
	s_barrier
	s_add_i32 s26, s60, s39
	v_lshl_add_u64 v[164:165], v[164:165], 0, s[18:19]
	s_mov_b32 m0, s26
	ds_read_b128 v[184:187], v169 offset:49152
	ds_read_b128 v[188:191], v169 offset:50176
	ds_read_b128 v[192:195], v169 offset:51200
	ds_read_b128 v[196:199], v169 offset:52224
	ds_read_b128 v[200:203], v169 offset:53248
	ds_read_b128 v[204:207], v169 offset:54272
	ds_read_b128 v[208:211], v169 offset:55296
	ds_read_b128 v[212:215], v169 offset:56320
	global_load_lds_dwordx4 v[164:165], off
	s_add_i32 m0, s26, 0x2000
	s_add_u32 s10, s10, 0x40080
	v_lshl_add_u64 v[164:165], v[216:217], 0, s[18:19]
	s_addc_u32 s11, s11, 0
	s_add_i32 s26, s61, s39
	global_load_lds_dwordx4 v[164:165], off
	v_lshl_add_u64 v[164:165], s[10:11], 0, v[148:149]
	s_mov_b32 m0, s26
	s_nop 0
	global_load_lds_dwordx4 v[164:165], off
	v_lshl_add_u64 v[164:165], s[10:11], 0, v[152:153]
	s_add_i32 m0, s26, 0x2000
	s_nop 0
	global_load_lds_dwordx4 v[164:165], off
	v_lshl_add_u64 v[164:165], v[218:219], 0, s[18:19]
	s_mov_b32 m0, s91
	s_nop 0
	global_load_lds_dwordx4 v[164:165], off
	v_lshl_add_u64 v[164:165], v[220:221], 0, s[18:19]
	s_mov_b32 m0, s92
	s_nop 0
	global_load_lds_dwordx4 v[164:165], off
	s_waitcnt vmcnt(8)
	s_waitcnt lgkmcnt(0)
	s_barrier
	s_waitcnt lgkmcnt(0)
	v_mfma_f32_16x16x32_bf16 v[62:65], v[130:133], v[184:187], v[62:65]
	v_mfma_f32_16x16x32_bf16 v[58:61], v[138:141], v[184:187], v[58:61]
	v_mfma_f32_16x16x32_bf16 v[46:49], v[130:133], v[192:195], v[46:49]
	v_mfma_f32_16x16x32_bf16 v[42:45], v[138:141], v[192:195], v[42:45]
	v_mfma_f32_16x16x32_bf16 v[30:33], v[130:133], v[200:203], v[30:33]
	v_mfma_f32_16x16x32_bf16 v[26:29], v[138:141], v[200:203], v[26:29]
	v_mfma_f32_16x16x32_bf16 v[14:17], v[130:133], v[208:211], v[14:17]
	v_mfma_f32_16x16x32_bf16 v[10:13], v[138:141], v[208:211], v[10:13]
	v_mfma_f32_16x16x32_bf16 v[62:65], v[134:137], v[188:191], v[62:65]
	v_mfma_f32_16x16x32_bf16 v[58:61], v[142:145], v[188:191], v[58:61]
	v_mfma_f32_16x16x32_bf16 v[46:49], v[134:137], v[196:199], v[46:49]
	v_mfma_f32_16x16x32_bf16 v[42:45], v[142:145], v[196:199], v[42:45]
	v_mfma_f32_16x16x32_bf16 v[30:33], v[134:137], v[204:207], v[30:33]
	v_mfma_f32_16x16x32_bf16 v[26:29], v[142:145], v[204:207], v[26:29]
	v_mfma_f32_16x16x32_bf16 v[14:17], v[134:137], v[212:215], v[14:17]
	v_mfma_f32_16x16x32_bf16 v[10:13], v[142:145], v[212:215], v[10:13]
	v_mfma_f32_16x16x32_bf16 v[54:57], v[160:163], v[184:187], v[54:57]
	v_mfma_f32_16x16x32_bf16 v[50:53], v[176:179], v[184:187], v[50:53]
	v_mfma_f32_16x16x32_bf16 v[38:41], v[160:163], v[192:195], v[38:41]
	v_mfma_f32_16x16x32_bf16 v[34:37], v[176:179], v[192:195], v[34:37]
	v_mfma_f32_16x16x32_bf16 v[22:25], v[160:163], v[200:203], v[22:25]
	v_mfma_f32_16x16x32_bf16 v[18:21], v[176:179], v[200:203], v[18:21]
	v_mfma_f32_16x16x32_bf16 v[6:9], v[160:163], v[208:211], v[6:9]
	v_mfma_f32_16x16x32_bf16 v[2:5], v[176:179], v[208:211], v[2:5]
	v_mfma_f32_16x16x32_bf16 v[54:57], v[172:175], v[188:191], v[54:57]
	v_mfma_f32_16x16x32_bf16 v[50:53], v[180:183], v[188:191], v[50:53]
	v_mfma_f32_16x16x32_bf16 v[38:41], v[172:175], v[196:199], v[38:41]
	v_mfma_f32_16x16x32_bf16 v[34:37], v[180:183], v[196:199], v[34:37]
	v_mfma_f32_16x16x32_bf16 v[22:25], v[172:175], v[204:207], v[22:25]
	v_mfma_f32_16x16x32_bf16 v[18:21], v[180:183], v[204:207], v[18:21]
	v_mfma_f32_16x16x32_bf16 v[6:9], v[172:175], v[212:215], v[6:9]
	v_mfma_f32_16x16x32_bf16 v[2:5], v[180:183], v[212:215], v[2:5]
	s_barrier
	s_add_i32 s51, s51, 2
	s_add_u32 s7, s7, 0x100
	s_addc_u32 s31, s31, 0
	s_add_u32 s8, s8, 0x100
	s_addc_u32 s9, s9, 0
.LBB0_953:
	ds_read_b128 v[130:133], v167
	ds_read_b128 v[134:137], v167 offset:1024
	ds_read_b128 v[138:141], v167 offset:2048
	ds_read_b128 v[142:145], v167 offset:3072
	ds_read_b128 v[160:163], v168
	ds_read_b128 v[172:175], v168 offset:1024
	ds_read_b128 v[176:179], v168 offset:2048
	ds_read_b128 v[180:183], v168 offset:3072
	s_add_u32 s10, s8, 0xfffc0080
	s_addc_u32 s11, s9, -1
	s_cmp_eq_u32 s51, 12
	s_cselect_b32 s59, s53, s11
	s_cselect_b32 s58, s52, s10
	s_cselect_b32 s11, s57, s31
	s_cselect_b32 s10, s56, s7
	v_lshl_add_u64 v[164:165], s[8:9], 0, v[158:159]
	s_add_i32 m0, s84, 0xc000
	ds_read_b128 v[184:187], v169
	ds_read_b128 v[188:191], v169 offset:1024
	ds_read_b128 v[192:195], v169 offset:2048
	ds_read_b128 v[196:199], v169 offset:3072
	ds_read_b128 v[200:203], v169 offset:4096
	ds_read_b128 v[204:207], v169 offset:5120
	ds_read_b128 v[208:211], v169 offset:6144
	ds_read_b128 v[212:215], v169 offset:7168
	global_load_lds_dwordx4 v[164:165], off
	v_lshl_add_u64 v[164:165], s[8:9], 0, v[156:157]
	s_add_i32 m0, s84, 0xe000
	s_nop 0
	global_load_lds_dwordx4 v[164:165], off
	s_waitcnt vmcnt(8)
	s_waitcnt lgkmcnt(0)
	s_barrier
	s_waitcnt lgkmcnt(0)
	v_mfma_f32_16x16x32_bf16 v[126:129], v[130:133], v[184:187], v[126:129]
	v_mfma_f32_16x16x32_bf16 v[122:125], v[138:141], v[184:187], v[122:125]
	v_mfma_f32_16x16x32_bf16 v[110:113], v[130:133], v[192:195], v[110:113]
	v_mfma_f32_16x16x32_bf16 v[106:109], v[138:141], v[192:195], v[106:109]
	v_mfma_f32_16x16x32_bf16 v[94:97], v[130:133], v[200:203], v[94:97]
	v_mfma_f32_16x16x32_bf16 v[90:93], v[138:141], v[200:203], v[90:93]
	v_mfma_f32_16x16x32_bf16 v[78:81], v[130:133], v[208:211], v[78:81]
	v_mfma_f32_16x16x32_bf16 v[74:77], v[138:141], v[208:211], v[74:77]
	v_mfma_f32_16x16x32_bf16 v[126:129], v[134:137], v[188:191], v[126:129]
	v_mfma_f32_16x16x32_bf16 v[122:125], v[142:145], v[188:191], v[122:125]
	v_mfma_f32_16x16x32_bf16 v[110:113], v[134:137], v[196:199], v[110:113]
	v_mfma_f32_16x16x32_bf16 v[106:109], v[142:145], v[196:199], v[106:109]
	v_mfma_f32_16x16x32_bf16 v[94:97], v[134:137], v[204:207], v[94:97]
	v_mfma_f32_16x16x32_bf16 v[90:93], v[142:145], v[204:207], v[90:93]
	v_mfma_f32_16x16x32_bf16 v[78:81], v[134:137], v[212:215], v[78:81]
	v_mfma_f32_16x16x32_bf16 v[74:77], v[142:145], v[212:215], v[74:77]
	v_mfma_f32_16x16x32_bf16 v[118:121], v[160:163], v[184:187], v[118:121]
	v_mfma_f32_16x16x32_bf16 v[114:117], v[176:179], v[184:187], v[114:117]
	v_mfma_f32_16x16x32_bf16 v[102:105], v[160:163], v[192:195], v[102:105]
	v_mfma_f32_16x16x32_bf16 v[98:101], v[176:179], v[192:195], v[98:101]
	v_mfma_f32_16x16x32_bf16 v[86:89], v[160:163], v[200:203], v[86:89]
	v_mfma_f32_16x16x32_bf16 v[82:85], v[176:179], v[200:203], v[82:85]
	v_mfma_f32_16x16x32_bf16 v[70:73], v[160:163], v[208:211], v[70:73]
	v_mfma_f32_16x16x32_bf16 v[66:69], v[176:179], v[208:211], v[66:69]
	v_mfma_f32_16x16x32_bf16 v[118:121], v[172:175], v[188:191], v[118:121]
	v_mfma_f32_16x16x32_bf16 v[114:117], v[180:183], v[188:191], v[114:117]
	v_mfma_f32_16x16x32_bf16 v[102:105], v[172:175], v[196:199], v[102:105]
	v_mfma_f32_16x16x32_bf16 v[98:101], v[180:183], v[196:199], v[98:101]
	v_mfma_f32_16x16x32_bf16 v[86:89], v[172:175], v[204:207], v[86:89]
	v_mfma_f32_16x16x32_bf16 v[82:85], v[180:183], v[204:207], v[82:85]
	v_mfma_f32_16x16x32_bf16 v[70:73], v[172:175], v[212:215], v[70:73]
	v_mfma_f32_16x16x32_bf16 v[66:69], v[180:183], v[212:215], v[66:69]
	s_barrier
	s_add_i32 s26, s94, s39
	v_lshl_add_u64 v[164:165], s[10:11], 0, v[148:149]
	s_mov_b32 m0, s26
	ds_read_b128 v[184:187], v169 offset:16384
	ds_read_b128 v[188:191], v169 offset:17408
	ds_read_b128 v[192:195], v169 offset:18432
	ds_read_b128 v[196:199], v169 offset:19456
	ds_read_b128 v[200:203], v169 offset:20480
	ds_read_b128 v[204:207], v169 offset:21504
	ds_read_b128 v[208:211], v169 offset:22528
	ds_read_b128 v[212:215], v169 offset:23552
	global_load_lds_dwordx4 v[164:165], off
	s_add_i32 m0, s26, 0x2000
	s_add_u32 s26, s10, 0x40000
	v_lshl_add_u64 v[216:217], s[10:11], 0, v[152:153]
	s_addc_u32 s27, s11, 0
	s_add_i32 s60, s95, s39
	global_load_lds_dwordx4 v[216:217], off
	v_lshl_add_u64 v[218:219], s[26:27], 0, v[148:149]
	s_mov_b32 m0, s60
	v_lshl_add_u64 v[220:221], s[58:59], 0, v[150:151]
	global_load_lds_dwordx4 v[218:219], off
	v_lshl_add_u64 v[218:219], s[26:27], 0, v[152:153]
	s_add_i32 m0, s60, 0x2000
	s_nop 0
	global_load_lds_dwordx4 v[218:219], off
	v_lshl_add_u64 v[218:219], s[58:59], 0, v[146:147]
	s_mov_b32 m0, s84
	s_nop 0
	global_load_lds_dwordx4 v[218:219], off
	s_mov_b32 m0, s85
	s_nop 0
	global_load_lds_dwordx4 v[220:221], off
	s_waitcnt vmcnt(8)
	s_waitcnt lgkmcnt(0)
	s_barrier
	s_waitcnt lgkmcnt(0)
	v_mfma_f32_16x16x32_bf16 v[62:65], v[130:133], v[184:187], v[62:65]
	v_mfma_f32_16x16x32_bf16 v[58:61], v[138:141], v[184:187], v[58:61]
	v_mfma_f32_16x16x32_bf16 v[46:49], v[130:133], v[192:195], v[46:49]
	v_mfma_f32_16x16x32_bf16 v[42:45], v[138:141], v[192:195], v[42:45]
	v_mfma_f32_16x16x32_bf16 v[30:33], v[130:133], v[200:203], v[30:33]
	v_mfma_f32_16x16x32_bf16 v[26:29], v[138:141], v[200:203], v[26:29]
	v_mfma_f32_16x16x32_bf16 v[14:17], v[130:133], v[208:211], v[14:17]
	v_mfma_f32_16x16x32_bf16 v[10:13], v[138:141], v[208:211], v[10:13]
	v_mfma_f32_16x16x32_bf16 v[62:65], v[134:137], v[188:191], v[62:65]
	v_mfma_f32_16x16x32_bf16 v[58:61], v[142:145], v[188:191], v[58:61]
	v_mfma_f32_16x16x32_bf16 v[46:49], v[134:137], v[196:199], v[46:49]
	v_mfma_f32_16x16x32_bf16 v[42:45], v[142:145], v[196:199], v[42:45]
	v_mfma_f32_16x16x32_bf16 v[30:33], v[134:137], v[204:207], v[30:33]
	v_mfma_f32_16x16x32_bf16 v[26:29], v[142:145], v[204:207], v[26:29]
	v_mfma_f32_16x16x32_bf16 v[14:17], v[134:137], v[212:215], v[14:17]
	v_mfma_f32_16x16x32_bf16 v[10:13], v[142:145], v[212:215], v[10:13]
	v_mfma_f32_16x16x32_bf16 v[54:57], v[160:163], v[184:187], v[54:57]
	v_mfma_f32_16x16x32_bf16 v[50:53], v[176:179], v[184:187], v[50:53]
	v_mfma_f32_16x16x32_bf16 v[38:41], v[160:163], v[192:195], v[38:41]
	v_mfma_f32_16x16x32_bf16 v[34:37], v[176:179], v[192:195], v[34:37]
	v_mfma_f32_16x16x32_bf16 v[22:25], v[160:163], v[200:203], v[22:25]
	v_mfma_f32_16x16x32_bf16 v[18:21], v[176:179], v[200:203], v[18:21]
	v_mfma_f32_16x16x32_bf16 v[6:9], v[160:163], v[208:211], v[6:9]
	v_mfma_f32_16x16x32_bf16 v[2:5], v[176:179], v[208:211], v[2:5]
	v_mfma_f32_16x16x32_bf16 v[54:57], v[172:175], v[188:191], v[54:57]
	v_mfma_f32_16x16x32_bf16 v[50:53], v[180:183], v[188:191], v[50:53]
	v_mfma_f32_16x16x32_bf16 v[38:41], v[172:175], v[196:199], v[38:41]
	v_mfma_f32_16x16x32_bf16 v[34:37], v[180:183], v[196:199], v[34:37]
	v_mfma_f32_16x16x32_bf16 v[22:25], v[172:175], v[204:207], v[22:25]
	v_mfma_f32_16x16x32_bf16 v[18:21], v[180:183], v[204:207], v[18:21]
	v_mfma_f32_16x16x32_bf16 v[6:9], v[172:175], v[212:215], v[6:9]
	v_mfma_f32_16x16x32_bf16 v[2:5], v[180:183], v[212:215], v[2:5]
	s_barrier
	s_add_i32 s60, 0, 0x18000
	v_add_u32_e32 v1, s60, v166
	s_add_i32 s61, 0, 0x1c000
	ds_read_b128 v[130:133], v1
	ds_read_b128 v[134:137], v1 offset:1024
	ds_read_b128 v[138:141], v1 offset:2048
	ds_read_b128 v[142:145], v1 offset:3072
	v_add_u32_e32 v1, s61, v166
	ds_read_b128 v[160:163], v1
	ds_read_b128 v[172:175], v1 offset:1024
	ds_read_b128 v[176:179], v1 offset:2048
	ds_read_b128 v[180:183], v1 offset:3072
	s_add_u32 s26, s58, 0x40000
	s_addc_u32 s27, s59, 0
	s_mov_b32 m0, s86
	v_lshl_add_u64 v[222:223], s[26:27], 0, v[146:147]
	ds_read_b128 v[184:187], v169 offset:32768
	ds_read_b128 v[188:191], v169 offset:33792
	ds_read_b128 v[192:195], v169 offset:34816
	ds_read_b128 v[196:199], v169 offset:35840
	ds_read_b128 v[200:203], v169 offset:36864
	ds_read_b128 v[204:207], v169 offset:37888
	ds_read_b128 v[208:211], v169 offset:38912
	ds_read_b128 v[212:215], v169 offset:39936
	global_load_lds_dwordx4 v[222:223], off
	v_lshl_add_u64 v[222:223], s[26:27], 0, v[150:151]
	s_mov_b32 m0, s87
	s_nop 0
	global_load_lds_dwordx4 v[222:223], off
	s_waitcnt vmcnt(8)
	s_waitcnt lgkmcnt(0)
	s_barrier
	s_waitcnt lgkmcnt(0)
	v_mfma_f32_16x16x32_bf16 v[126:129], v[130:133], v[184:187], v[126:129]
	v_mfma_f32_16x16x32_bf16 v[122:125], v[138:141], v[184:187], v[122:125]
	v_mfma_f32_16x16x32_bf16 v[110:113], v[130:133], v[192:195], v[110:113]
	v_mfma_f32_16x16x32_bf16 v[106:109], v[138:141], v[192:195], v[106:109]
	v_mfma_f32_16x16x32_bf16 v[94:97], v[130:133], v[200:203], v[94:97]
	v_mfma_f32_16x16x32_bf16 v[90:93], v[138:141], v[200:203], v[90:93]
	v_mfma_f32_16x16x32_bf16 v[78:81], v[130:133], v[208:211], v[78:81]
	v_mfma_f32_16x16x32_bf16 v[74:77], v[138:141], v[208:211], v[74:77]
	v_mfma_f32_16x16x32_bf16 v[126:129], v[134:137], v[188:191], v[126:129]
	v_mfma_f32_16x16x32_bf16 v[122:125], v[142:145], v[188:191], v[122:125]
	v_mfma_f32_16x16x32_bf16 v[110:113], v[134:137], v[196:199], v[110:113]
	v_mfma_f32_16x16x32_bf16 v[106:109], v[142:145], v[196:199], v[106:109]
	v_mfma_f32_16x16x32_bf16 v[94:97], v[134:137], v[204:207], v[94:97]
	v_mfma_f32_16x16x32_bf16 v[90:93], v[142:145], v[204:207], v[90:93]
	v_mfma_f32_16x16x32_bf16 v[78:81], v[134:137], v[212:215], v[78:81]
	v_mfma_f32_16x16x32_bf16 v[74:77], v[142:145], v[212:215], v[74:77]
	v_mfma_f32_16x16x32_bf16 v[118:121], v[160:163], v[184:187], v[118:121]
	v_mfma_f32_16x16x32_bf16 v[114:117], v[176:179], v[184:187], v[114:117]
	v_mfma_f32_16x16x32_bf16 v[102:105], v[160:163], v[192:195], v[102:105]
	v_mfma_f32_16x16x32_bf16 v[98:101], v[176:179], v[192:195], v[98:101]
	v_mfma_f32_16x16x32_bf16 v[86:89], v[160:163], v[200:203], v[86:89]
	v_mfma_f32_16x16x32_bf16 v[82:85], v[176:179], v[200:203], v[82:85]
	v_mfma_f32_16x16x32_bf16 v[70:73], v[160:163], v[208:211], v[70:73]
	v_mfma_f32_16x16x32_bf16 v[66:69], v[176:179], v[208:211], v[66:69]
	v_mfma_f32_16x16x32_bf16 v[118:121], v[172:175], v[188:191], v[118:121]
	v_mfma_f32_16x16x32_bf16 v[114:117], v[180:183], v[188:191], v[114:117]
	v_mfma_f32_16x16x32_bf16 v[102:105], v[172:175], v[196:199], v[102:105]
	v_mfma_f32_16x16x32_bf16 v[98:101], v[180:183], v[196:199], v[98:101]
	v_mfma_f32_16x16x32_bf16 v[86:89], v[172:175], v[204:207], v[86:89]
	v_mfma_f32_16x16x32_bf16 v[82:85], v[180:183], v[204:207], v[82:85]
	v_mfma_f32_16x16x32_bf16 v[70:73], v[172:175], v[212:215], v[70:73]
	v_mfma_f32_16x16x32_bf16 v[66:69], v[180:183], v[212:215], v[66:69]
	s_barrier
	s_add_i32 s26, s60, s39
	v_lshl_add_u64 v[164:165], v[164:165], 0, s[18:19]
	s_mov_b32 m0, s26
	ds_read_b128 v[184:187], v169 offset:49152
	ds_read_b128 v[188:191], v169 offset:50176
	ds_read_b128 v[192:195], v169 offset:51200
	ds_read_b128 v[196:199], v169 offset:52224
	ds_read_b128 v[200:203], v169 offset:53248
	ds_read_b128 v[204:207], v169 offset:54272
	ds_read_b128 v[208:211], v169 offset:55296
	ds_read_b128 v[212:215], v169 offset:56320
	global_load_lds_dwordx4 v[164:165], off
	s_add_i32 m0, s26, 0x2000
	s_add_u32 s10, s10, 0x40080
	v_lshl_add_u64 v[164:165], v[216:217], 0, s[18:19]
	s_addc_u32 s11, s11, 0
	s_add_i32 s26, s61, s39
	global_load_lds_dwordx4 v[164:165], off
	v_lshl_add_u64 v[164:165], s[10:11], 0, v[148:149]
	s_mov_b32 m0, s26
	s_nop 0
	global_load_lds_dwordx4 v[164:165], off
	v_lshl_add_u64 v[164:165], s[10:11], 0, v[152:153]
	s_add_i32 m0, s26, 0x2000
	s_nop 0
	global_load_lds_dwordx4 v[164:165], off
	v_lshl_add_u64 v[164:165], v[218:219], 0, s[18:19]
	s_mov_b32 m0, s91
	s_nop 0
	global_load_lds_dwordx4 v[164:165], off
	v_lshl_add_u64 v[164:165], v[220:221], 0, s[18:19]
	s_mov_b32 m0, s92
	s_nop 0
	global_load_lds_dwordx4 v[164:165], off
	s_waitcnt vmcnt(8)
	s_waitcnt lgkmcnt(0)
	s_barrier
	s_waitcnt lgkmcnt(0)
	v_mfma_f32_16x16x32_bf16 v[62:65], v[130:133], v[184:187], v[62:65]
	v_mfma_f32_16x16x32_bf16 v[58:61], v[138:141], v[184:187], v[58:61]
	v_mfma_f32_16x16x32_bf16 v[46:49], v[130:133], v[192:195], v[46:49]
	v_mfma_f32_16x16x32_bf16 v[42:45], v[138:141], v[192:195], v[42:45]
	v_mfma_f32_16x16x32_bf16 v[30:33], v[130:133], v[200:203], v[30:33]
	v_mfma_f32_16x16x32_bf16 v[26:29], v[138:141], v[200:203], v[26:29]
	v_mfma_f32_16x16x32_bf16 v[14:17], v[130:133], v[208:211], v[14:17]
	v_mfma_f32_16x16x32_bf16 v[10:13], v[138:141], v[208:211], v[10:13]
	v_mfma_f32_16x16x32_bf16 v[62:65], v[134:137], v[188:191], v[62:65]
	v_mfma_f32_16x16x32_bf16 v[58:61], v[142:145], v[188:191], v[58:61]
	v_mfma_f32_16x16x32_bf16 v[46:49], v[134:137], v[196:199], v[46:49]
	v_mfma_f32_16x16x32_bf16 v[42:45], v[142:145], v[196:199], v[42:45]
	v_mfma_f32_16x16x32_bf16 v[30:33], v[134:137], v[204:207], v[30:33]
	v_mfma_f32_16x16x32_bf16 v[26:29], v[142:145], v[204:207], v[26:29]
	v_mfma_f32_16x16x32_bf16 v[14:17], v[134:137], v[212:215], v[14:17]
	v_mfma_f32_16x16x32_bf16 v[10:13], v[142:145], v[212:215], v[10:13]
	v_mfma_f32_16x16x32_bf16 v[54:57], v[160:163], v[184:187], v[54:57]
	v_mfma_f32_16x16x32_bf16 v[50:53], v[176:179], v[184:187], v[50:53]
	v_mfma_f32_16x16x32_bf16 v[38:41], v[160:163], v[192:195], v[38:41]
	v_mfma_f32_16x16x32_bf16 v[34:37], v[176:179], v[192:195], v[34:37]
	v_mfma_f32_16x16x32_bf16 v[22:25], v[160:163], v[200:203], v[22:25]
	v_mfma_f32_16x16x32_bf16 v[18:21], v[176:179], v[200:203], v[18:21]
	v_mfma_f32_16x16x32_bf16 v[6:9], v[160:163], v[208:211], v[6:9]
	v_mfma_f32_16x16x32_bf16 v[2:5], v[176:179], v[208:211], v[2:5]
	v_mfma_f32_16x16x32_bf16 v[54:57], v[172:175], v[188:191], v[54:57]
	v_mfma_f32_16x16x32_bf16 v[50:53], v[180:183], v[188:191], v[50:53]
	v_mfma_f32_16x16x32_bf16 v[38:41], v[172:175], v[196:199], v[38:41]
	v_mfma_f32_16x16x32_bf16 v[34:37], v[180:183], v[196:199], v[34:37]
	v_mfma_f32_16x16x32_bf16 v[22:25], v[172:175], v[204:207], v[22:25]
	v_mfma_f32_16x16x32_bf16 v[18:21], v[180:183], v[204:207], v[18:21]
	v_mfma_f32_16x16x32_bf16 v[6:9], v[172:175], v[212:215], v[6:9]
	v_mfma_f32_16x16x32_bf16 v[2:5], v[180:183], v[212:215], v[2:5]
	s_barrier
	s_add_i32 s51, s51, 2
	s_add_u32 s7, s7, 0x100
	s_addc_u32 s31, s31, 0
	s_add_u32 s8, s8, 0x100
	s_addc_u32 s9, s9, 0
	s_cmp_gt_u32 s51, 13
	s_cbranch_scc0 .LBB0_953
	s_and_b64 vcc, exec, s[14:15]
	s_cbranch_vccz .LBB0_956
	s_barrier

.LBB0_1290:
	s_add_u32 s8, s56, 0x100
	s_addc_u32 s45, s57, 0
	s_add_u32 s6, s52, 0x40080
	v_mov_b32_e32 v8, 0
	s_addc_u32 s7, s53, 0
	s_mov_b32 s55, -2
	s_waitcnt lgkmcnt(0)
	ds_read_b128 v[0:3], v96
	ds_read_b128 v[4:7], v96 offset:1024
	ds_read_b128 v[84:87], v96 offset:2048
	ds_read_b128 v[100:103], v96 offset:3072
	s_add_u32 s26, s6, 0xfffc0080
	s_addc_u32 s27, s7, -1
	s_cmp_eq_u32 s55, 12
	s_cselect_b32 s53, s47, s27
	s_cselect_b32 s52, s46, s26
	s_cselect_b32 s27, s49, s45
	s_cselect_b32 s26, s48, s8
	v_lshl_add_u64 v[88:89], s[6:7], 0, v[82:83]
	s_add_i32 m0, s28, 0xc000
	ds_read_b128 v[104:107], v97
	ds_read_b128 v[108:111], v97 offset:1024
	ds_read_b128 v[112:115], v97 offset:2048
	ds_read_b128 v[116:119], v97 offset:3072
	ds_read_b128 v[120:123], v97 offset:4096
	ds_read_b128 v[124:127], v97 offset:5120
	ds_read_b128 v[128:131], v97 offset:6144
	ds_read_b128 v[132:135], v97 offset:7168
	global_load_lds_dwordx4 v[88:89], off
	v_lshl_add_u64 v[88:89], s[6:7], 0, v[80:81]
	s_add_i32 m0, s28, 0xe000
	s_nop 0
	global_load_lds_dwordx4 v[88:89], off
	s_waitcnt vmcnt(6)
	s_waitcnt lgkmcnt(0)
	s_barrier
	s_waitcnt lgkmcnt(0)
	v_mfma_f32_16x16x32_bf16 v[68:71], v[0:3], v[104:107], 0
	v_mfma_f32_16x16x32_bf16 v[64:67], v[84:87], v[104:107], 0
	v_mfma_f32_16x16x32_bf16 v[60:63], v[0:3], v[112:115], 0
	v_mfma_f32_16x16x32_bf16 v[56:59], v[84:87], v[112:115], 0
	v_mfma_f32_16x16x32_bf16 v[52:55], v[0:3], v[120:123], 0
	v_mfma_f32_16x16x32_bf16 v[48:51], v[84:87], v[120:123], 0
	v_mfma_f32_16x16x32_bf16 v[44:47], v[0:3], v[128:131], 0
	v_mfma_f32_16x16x32_bf16 v[40:43], v[84:87], v[128:131], 0
	v_mfma_f32_16x16x32_bf16 v[68:71], v[4:7], v[108:111], v[68:71]
	v_mfma_f32_16x16x32_bf16 v[64:67], v[100:103], v[108:111], v[64:67]
	v_mfma_f32_16x16x32_bf16 v[60:63], v[4:7], v[116:119], v[60:63]
	v_mfma_f32_16x16x32_bf16 v[56:59], v[100:103], v[116:119], v[56:59]
	v_mfma_f32_16x16x32_bf16 v[52:55], v[4:7], v[124:127], v[52:55]
	v_mfma_f32_16x16x32_bf16 v[48:51], v[100:103], v[124:127], v[48:51]
	v_mfma_f32_16x16x32_bf16 v[44:47], v[4:7], v[132:135], v[44:47]
	v_mfma_f32_16x16x32_bf16 v[40:43], v[100:103], v[132:135], v[40:43]
	s_barrier
	s_add_i32 s56, s68, s39
	v_lshl_add_u64 v[88:89], s[26:27], 0, v[74:75]
	s_mov_b32 m0, s56
	ds_read_b128 v[104:107], v97 offset:16384
	ds_read_b128 v[108:111], v97 offset:17408
	ds_read_b128 v[112:115], v97 offset:18432
	ds_read_b128 v[116:119], v97 offset:19456
	ds_read_b128 v[120:123], v97 offset:20480
	ds_read_b128 v[124:127], v97 offset:21504
	ds_read_b128 v[128:131], v97 offset:22528
	ds_read_b128 v[132:135], v97 offset:23552
	global_load_lds_dwordx4 v[88:89], off
	v_lshl_add_u64 v[136:137], s[26:27], 0, v[78:79]
	s_add_i32 m0, s56, 0x2000
	v_lshl_add_u64 v[138:139], s[52:53], 0, v[72:73]
	global_load_lds_dwordx4 v[136:137], off
	s_mov_b32 m0, s28
	v_lshl_add_u64 v[140:141], s[52:53], 0, v[76:77]
	global_load_lds_dwordx4 v[138:139], off
	s_mov_b32 m0, s29
	s_nop 0
	global_load_lds_dwordx4 v[140:141], off
	s_waitcnt vmcnt(6)
	s_waitcnt lgkmcnt(0)
	s_barrier
	s_waitcnt lgkmcnt(0)
	v_mfma_f32_16x16x32_bf16 v[36:39], v[0:3], v[104:107], 0
	v_mfma_f32_16x16x32_bf16 v[32:35], v[84:87], v[104:107], 0
	v_mfma_f32_16x16x32_bf16 v[28:31], v[0:3], v[112:115], 0
	v_mfma_f32_16x16x32_bf16 v[24:27], v[84:87], v[112:115], 0
	v_mfma_f32_16x16x32_bf16 v[20:23], v[0:3], v[120:123], 0
	v_mfma_f32_16x16x32_bf16 v[16:19], v[84:87], v[120:123], 0
	v_mfma_f32_16x16x32_bf16 v[0:3], v[0:3], v[128:131], 0
	v_mfma_f32_16x16x32_bf16 v[36:39], v[4:7], v[108:111], v[36:39]
	v_mfma_f32_16x16x32_bf16 v[32:35], v[100:103], v[108:111], v[32:35]
	v_mfma_f32_16x16x32_bf16 v[28:31], v[4:7], v[116:119], v[28:31]
	v_mfma_f32_16x16x32_bf16 v[24:27], v[100:103], v[116:119], v[24:27]
	v_mfma_f32_16x16x32_bf16 v[20:23], v[4:7], v[124:127], v[20:23]
	v_mfma_f32_16x16x32_bf16 v[16:19], v[100:103], v[124:127], v[16:19]
	v_mfma_f32_16x16x32_bf16 v[0:3], v[4:7], v[132:135], v[0:3]
	v_mfma_f32_16x16x32_bf16 v[4:7], v[84:87], v[128:131], 0
	v_mfma_f32_16x16x32_bf16 v[4:7], v[100:103], v[132:135], v[4:7]
	s_barrier
	s_add_i32 s56, 0, 0x18000
	v_add_u32_e32 v90, s56, v91
	ds_read_b128 v[8:11], v90
	ds_read_b128 v[12:15], v90 offset:1024
	ds_read_b128 v[84:87], v90 offset:2048
	ds_read_b128 v[100:103], v90 offset:3072
	s_add_u32 s26, s52, 0x40000
	s_addc_u32 s27, s53, 0
	s_mov_b32 m0, s30
	v_lshl_add_u64 v[142:143], s[26:27], 0, v[72:73]
	ds_read_b128 v[104:107], v97 offset:32768
	ds_read_b128 v[108:111], v97 offset:33792
	ds_read_b128 v[112:115], v97 offset:34816
	ds_read_b128 v[116:119], v97 offset:35840
	ds_read_b128 v[120:123], v97 offset:36864
	ds_read_b128 v[124:127], v97 offset:37888
	ds_read_b128 v[128:131], v97 offset:38912
	ds_read_b128 v[132:135], v97 offset:39936
	global_load_lds_dwordx4 v[142:143], off
	v_lshl_add_u64 v[142:143], s[26:27], 0, v[76:77]
	s_mov_b32 m0, s31
	s_nop 0
	global_load_lds_dwordx4 v[142:143], off
	s_waitcnt vmcnt(6)
	s_waitcnt lgkmcnt(0)
	s_barrier
	s_waitcnt lgkmcnt(0)
	v_mfma_f32_16x16x32_bf16 v[68:71], v[8:11], v[104:107], v[68:71]
	v_mfma_f32_16x16x32_bf16 v[64:67], v[84:87], v[104:107], v[64:67]
	v_mfma_f32_16x16x32_bf16 v[60:63], v[8:11], v[112:115], v[60:63]
	v_mfma_f32_16x16x32_bf16 v[56:59], v[84:87], v[112:115], v[56:59]
	v_mfma_f32_16x16x32_bf16 v[52:55], v[8:11], v[120:123], v[52:55]
	v_mfma_f32_16x16x32_bf16 v[48:51], v[84:87], v[120:123], v[48:51]
	v_mfma_f32_16x16x32_bf16 v[44:47], v[8:11], v[128:131], v[44:47]
	v_mfma_f32_16x16x32_bf16 v[40:43], v[84:87], v[128:131], v[40:43]
	v_mfma_f32_16x16x32_bf16 v[68:71], v[12:15], v[108:111], v[68:71]
	v_mfma_f32_16x16x32_bf16 v[64:67], v[100:103], v[108:111], v[64:67]
	v_mfma_f32_16x16x32_bf16 v[60:63], v[12:15], v[116:119], v[60:63]
	v_mfma_f32_16x16x32_bf16 v[56:59], v[100:103], v[116:119], v[56:59]
	v_mfma_f32_16x16x32_bf16 v[52:55], v[12:15], v[124:127], v[52:55]
	v_mfma_f32_16x16x32_bf16 v[48:51], v[100:103], v[124:127], v[48:51]
	v_mfma_f32_16x16x32_bf16 v[44:47], v[12:15], v[132:135], v[44:47]
	v_mfma_f32_16x16x32_bf16 v[40:43], v[100:103], v[132:135], v[40:43]
	s_barrier
	s_add_i32 s26, s56, s39
	v_lshl_add_u64 v[88:89], v[88:89], 0, s[10:11]
	s_mov_b32 m0, s26
	ds_read_b128 v[104:107], v97 offset:49152
	ds_read_b128 v[108:111], v97 offset:50176
	ds_read_b128 v[112:115], v97 offset:51200
	ds_read_b128 v[116:119], v97 offset:52224
	ds_read_b128 v[120:123], v97 offset:53248
	ds_read_b128 v[124:127], v97 offset:54272
	ds_read_b128 v[128:131], v97 offset:55296
	ds_read_b128 v[132:135], v97 offset:56320
	global_load_lds_dwordx4 v[88:89], off
	v_lshl_add_u64 v[88:89], v[136:137], 0, s[10:11]
	s_add_i32 m0, s26, 0x2000
	s_nop 0
	global_load_lds_dwordx4 v[88:89], off
	v_lshl_add_u64 v[88:89], v[138:139], 0, s[10:11]
	s_mov_b32 m0, s62
	s_nop 0
	global_load_lds_dwordx4 v[88:89], off
	v_lshl_add_u64 v[88:89], v[140:141], 0, s[10:11]
	s_mov_b32 m0, s63
	s_nop 0
	global_load_lds_dwordx4 v[88:89], off
	s_waitcnt vmcnt(6)
	s_waitcnt lgkmcnt(0)
	s_barrier
	s_waitcnt lgkmcnt(0)
	v_mfma_f32_16x16x32_bf16 v[36:39], v[8:11], v[104:107], v[36:39]
	v_mfma_f32_16x16x32_bf16 v[28:31], v[8:11], v[112:115], v[28:31]
	v_mfma_f32_16x16x32_bf16 v[20:23], v[8:11], v[120:123], v[20:23]
	v_mfma_f32_16x16x32_bf16 v[0:3], v[8:11], v[128:131], v[0:3]
	v_mfma_f32_16x16x32_bf16 v[36:39], v[12:15], v[108:111], v[36:39]
	v_mfma_f32_16x16x32_bf16 v[32:35], v[84:87], v[104:107], v[32:35]
	v_mfma_f32_16x16x32_bf16 v[28:31], v[12:15], v[116:119], v[28:31]
	v_mfma_f32_16x16x32_bf16 v[24:27], v[84:87], v[112:115], v[24:27]
	v_mfma_f32_16x16x32_bf16 v[20:23], v[12:15], v[124:127], v[20:23]
	v_mfma_f32_16x16x32_bf16 v[16:19], v[84:87], v[120:123], v[16:19]
	v_mfma_f32_16x16x32_bf16 v[12:15], v[12:15], v[132:135], v[0:3]
	v_mfma_f32_16x16x32_bf16 v[0:3], v[84:87], v[128:131], v[4:7]
	v_mfma_f32_16x16x32_bf16 v[32:35], v[100:103], v[108:111], v[32:35]
	v_mfma_f32_16x16x32_bf16 v[24:27], v[100:103], v[116:119], v[24:27]
	v_mfma_f32_16x16x32_bf16 v[16:19], v[100:103], v[124:127], v[16:19]
	v_mfma_f32_16x16x32_bf16 v[8:11], v[100:103], v[132:135], v[0:3]
	s_barrier
	s_add_i32 s55, s55, 2
	s_add_u32 s8, s8, 0x100
	s_addc_u32 s45, s45, 0
	s_add_u32 s6, s6, 0x100
	s_addc_u32 s7, s7, 0
.LBB0_1291:
	s_waitcnt lgkmcnt(0)
	ds_read_b128 v[0:3], v96
	ds_read_b128 v[4:7], v96 offset:1024
	ds_read_b128 v[84:87], v96 offset:2048
	ds_read_b128 v[100:103], v96 offset:3072
	s_add_u32 s26, s6, 0xfffc0080
	s_addc_u32 s27, s7, -1
	s_cmp_eq_u32 s55, 12
	s_cselect_b32 s53, s47, s27
	s_cselect_b32 s52, s46, s26
	s_cselect_b32 s27, s49, s45
	s_cselect_b32 s26, s48, s8
	v_lshl_add_u64 v[88:89], s[6:7], 0, v[82:83]
	s_add_i32 m0, s28, 0xc000
	ds_read_b128 v[104:107], v97
	ds_read_b128 v[108:111], v97 offset:1024
	ds_read_b128 v[112:115], v97 offset:2048
	ds_read_b128 v[116:119], v97 offset:3072
	ds_read_b128 v[120:123], v97 offset:4096
	ds_read_b128 v[124:127], v97 offset:5120
	ds_read_b128 v[128:131], v97 offset:6144
	ds_read_b128 v[132:135], v97 offset:7168
	global_load_lds_dwordx4 v[88:89], off
	v_lshl_add_u64 v[88:89], s[6:7], 0, v[80:81]
	s_add_i32 m0, s28, 0xe000
	s_nop 0
	global_load_lds_dwordx4 v[88:89], off
	s_waitcnt vmcnt(6)
	s_waitcnt lgkmcnt(0)
	s_barrier
	s_waitcnt lgkmcnt(0)
	v_mfma_f32_16x16x32_bf16 v[68:71], v[0:3], v[104:107], v[68:71]
	v_mfma_f32_16x16x32_bf16 v[64:67], v[84:87], v[104:107], v[64:67]
	v_mfma_f32_16x16x32_bf16 v[60:63], v[0:3], v[112:115], v[60:63]
	v_mfma_f32_16x16x32_bf16 v[56:59], v[84:87], v[112:115], v[56:59]
	v_mfma_f32_16x16x32_bf16 v[52:55], v[0:3], v[120:123], v[52:55]
	v_mfma_f32_16x16x32_bf16 v[48:51], v[84:87], v[120:123], v[48:51]
	v_mfma_f32_16x16x32_bf16 v[44:47], v[0:3], v[128:131], v[44:47]
	v_mfma_f32_16x16x32_bf16 v[40:43], v[84:87], v[128:131], v[40:43]
	v_mfma_f32_16x16x32_bf16 v[68:71], v[4:7], v[108:111], v[68:71]
	v_mfma_f32_16x16x32_bf16 v[64:67], v[100:103], v[108:111], v[64:67]
	v_mfma_f32_16x16x32_bf16 v[60:63], v[4:7], v[116:119], v[60:63]
	v_mfma_f32_16x16x32_bf16 v[56:59], v[100:103], v[116:119], v[56:59]
	v_mfma_f32_16x16x32_bf16 v[52:55], v[4:7], v[124:127], v[52:55]
	v_mfma_f32_16x16x32_bf16 v[48:51], v[100:103], v[124:127], v[48:51]
	v_mfma_f32_16x16x32_bf16 v[44:47], v[4:7], v[132:135], v[44:47]
	v_mfma_f32_16x16x32_bf16 v[40:43], v[100:103], v[132:135], v[40:43]
	s_barrier
	s_add_i32 s56, s68, s39
	v_lshl_add_u64 v[88:89], s[26:27], 0, v[74:75]
	s_mov_b32 m0, s56
	ds_read_b128 v[104:107], v97 offset:16384
	ds_read_b128 v[108:111], v97 offset:17408
	ds_read_b128 v[112:115], v97 offset:18432
	ds_read_b128 v[116:119], v97 offset:19456
	ds_read_b128 v[120:123], v97 offset:20480
	ds_read_b128 v[124:127], v97 offset:21504
	ds_read_b128 v[128:131], v97 offset:22528
	ds_read_b128 v[132:135], v97 offset:23552
	global_load_lds_dwordx4 v[88:89], off
	v_lshl_add_u64 v[136:137], s[26:27], 0, v[78:79]
	s_add_i32 m0, s56, 0x2000
	v_lshl_add_u64 v[138:139], s[52:53], 0, v[72:73]
	global_load_lds_dwordx4 v[136:137], off
	s_mov_b32 m0, s28
	v_lshl_add_u64 v[140:141], s[52:53], 0, v[76:77]
	global_load_lds_dwordx4 v[138:139], off
	s_mov_b32 m0, s29
	s_nop 0
	global_load_lds_dwordx4 v[140:141], off
	s_waitcnt vmcnt(6)
	s_waitcnt lgkmcnt(0)
	s_barrier
	s_waitcnt lgkmcnt(0)
	v_mfma_f32_16x16x32_bf16 v[36:39], v[0:3], v[104:107], v[36:39]
	v_mfma_f32_16x16x32_bf16 v[32:35], v[84:87], v[104:107], v[32:35]
	v_mfma_f32_16x16x32_bf16 v[28:31], v[0:3], v[112:115], v[28:31]
	v_mfma_f32_16x16x32_bf16 v[24:27], v[84:87], v[112:115], v[24:27]
	v_mfma_f32_16x16x32_bf16 v[20:23], v[0:3], v[120:123], v[20:23]
	v_mfma_f32_16x16x32_bf16 v[16:19], v[84:87], v[120:123], v[16:19]
	v_mfma_f32_16x16x32_bf16 v[0:3], v[0:3], v[128:131], v[12:15]
	v_mfma_f32_16x16x32_bf16 v[36:39], v[4:7], v[108:111], v[36:39]
	v_mfma_f32_16x16x32_bf16 v[32:35], v[100:103], v[108:111], v[32:35]
	v_mfma_f32_16x16x32_bf16 v[28:31], v[4:7], v[116:119], v[28:31]
	v_mfma_f32_16x16x32_bf16 v[24:27], v[100:103], v[116:119], v[24:27]
	v_mfma_f32_16x16x32_bf16 v[20:23], v[4:7], v[124:127], v[20:23]
	v_mfma_f32_16x16x32_bf16 v[16:19], v[100:103], v[124:127], v[16:19]
	v_mfma_f32_16x16x32_bf16 v[0:3], v[4:7], v[132:135], v[0:3]
	v_mfma_f32_16x16x32_bf16 v[4:7], v[84:87], v[128:131], v[8:11]
	v_mfma_f32_16x16x32_bf16 v[4:7], v[100:103], v[132:135], v[4:7]
	s_barrier
	s_add_i32 s56, 0, 0x18000
	v_add_u32_e32 v90, s56, v91
	ds_read_b128 v[8:11], v90
	ds_read_b128 v[12:15], v90 offset:1024
	ds_read_b128 v[84:87], v90 offset:2048
	ds_read_b128 v[100:103], v90 offset:3072
	s_add_u32 s26, s52, 0x40000
	s_addc_u32 s27, s53, 0
	s_mov_b32 m0, s30
	v_lshl_add_u64 v[142:143], s[26:27], 0, v[72:73]
	ds_read_b128 v[104:107], v97 offset:32768
	ds_read_b128 v[108:111], v97 offset:33792
	ds_read_b128 v[112:115], v97 offset:34816
	ds_read_b128 v[116:119], v97 offset:35840
	ds_read_b128 v[120:123], v97 offset:36864
	ds_read_b128 v[124:127], v97 offset:37888
	ds_read_b128 v[128:131], v97 offset:38912
	ds_read_b128 v[132:135], v97 offset:39936
	global_load_lds_dwordx4 v[142:143], off
	v_lshl_add_u64 v[142:143], s[26:27], 0, v[76:77]
	s_mov_b32 m0, s31
	s_nop 0
	global_load_lds_dwordx4 v[142:143], off
	s_waitcnt vmcnt(6)
	s_waitcnt lgkmcnt(0)
	s_barrier
	s_waitcnt lgkmcnt(0)
	v_mfma_f32_16x16x32_bf16 v[68:71], v[8:11], v[104:107], v[68:71]
	v_mfma_f32_16x16x32_bf16 v[64:67], v[84:87], v[104:107], v[64:67]
	v_mfma_f32_16x16x32_bf16 v[60:63], v[8:11], v[112:115], v[60:63]
	v_mfma_f32_16x16x32_bf16 v[56:59], v[84:87], v[112:115], v[56:59]
	v_mfma_f32_16x16x32_bf16 v[52:55], v[8:11], v[120:123], v[52:55]
	v_mfma_f32_16x16x32_bf16 v[48:51], v[84:87], v[120:123], v[48:51]
	v_mfma_f32_16x16x32_bf16 v[44:47], v[8:11], v[128:131], v[44:47]
	v_mfma_f32_16x16x32_bf16 v[40:43], v[84:87], v[128:131], v[40:43]
	v_mfma_f32_16x16x32_bf16 v[68:71], v[12:15], v[108:111], v[68:71]
	v_mfma_f32_16x16x32_bf16 v[64:67], v[100:103], v[108:111], v[64:67]
	v_mfma_f32_16x16x32_bf16 v[60:63], v[12:15], v[116:119], v[60:63]
	v_mfma_f32_16x16x32_bf16 v[56:59], v[100:103], v[116:119], v[56:59]
	v_mfma_f32_16x16x32_bf16 v[52:55], v[12:15], v[124:127], v[52:55]
	v_mfma_f32_16x16x32_bf16 v[48:51], v[100:103], v[124:127], v[48:51]
	v_mfma_f32_16x16x32_bf16 v[44:47], v[12:15], v[132:135], v[44:47]
	v_mfma_f32_16x16x32_bf16 v[40:43], v[100:103], v[132:135], v[40:43]
	s_barrier
	s_add_i32 s26, s56, s39
	v_lshl_add_u64 v[88:89], v[88:89], 0, s[10:11]
	s_mov_b32 m0, s26
	ds_read_b128 v[104:107], v97 offset:49152
	ds_read_b128 v[108:111], v97 offset:50176
	ds_read_b128 v[112:115], v97 offset:51200
	ds_read_b128 v[116:119], v97 offset:52224
	ds_read_b128 v[120:123], v97 offset:53248
	ds_read_b128 v[124:127], v97 offset:54272
	ds_read_b128 v[128:131], v97 offset:55296
	ds_read_b128 v[132:135], v97 offset:56320
	global_load_lds_dwordx4 v[88:89], off
	v_lshl_add_u64 v[88:89], v[136:137], 0, s[10:11]
	s_add_i32 m0, s26, 0x2000
	s_nop 0
	global_load_lds_dwordx4 v[88:89], off
	v_lshl_add_u64 v[88:89], v[138:139], 0, s[10:11]
	s_mov_b32 m0, s62
	s_nop 0
	global_load_lds_dwordx4 v[88:89], off
	v_lshl_add_u64 v[88:89], v[140:141], 0, s[10:11]
	s_mov_b32 m0, s63
	s_nop 0
	global_load_lds_dwordx4 v[88:89], off
	s_waitcnt vmcnt(6)
	s_waitcnt lgkmcnt(0)
	s_barrier
	s_waitcnt lgkmcnt(0)
	v_mfma_f32_16x16x32_bf16 v[36:39], v[8:11], v[104:107], v[36:39]
	v_mfma_f32_16x16x32_bf16 v[28:31], v[8:11], v[112:115], v[28:31]
	v_mfma_f32_16x16x32_bf16 v[20:23], v[8:11], v[120:123], v[20:23]
	v_mfma_f32_16x16x32_bf16 v[0:3], v[8:11], v[128:131], v[0:3]
	v_mfma_f32_16x16x32_bf16 v[36:39], v[12:15], v[108:111], v[36:39]
	v_mfma_f32_16x16x32_bf16 v[32:35], v[84:87], v[104:107], v[32:35]
	v_mfma_f32_16x16x32_bf16 v[28:31], v[12:15], v[116:119], v[28:31]
	v_mfma_f32_16x16x32_bf16 v[24:27], v[84:87], v[112:115], v[24:27]
	v_mfma_f32_16x16x32_bf16 v[20:23], v[12:15], v[124:127], v[20:23]
	v_mfma_f32_16x16x32_bf16 v[16:19], v[84:87], v[120:123], v[16:19]
	v_mfma_f32_16x16x32_bf16 v[12:15], v[12:15], v[132:135], v[0:3]
	v_mfma_f32_16x16x32_bf16 v[0:3], v[84:87], v[128:131], v[4:7]
	v_mfma_f32_16x16x32_bf16 v[32:35], v[100:103], v[108:111], v[32:35]
	v_mfma_f32_16x16x32_bf16 v[24:27], v[100:103], v[116:119], v[24:27]
	v_mfma_f32_16x16x32_bf16 v[16:19], v[100:103], v[124:127], v[16:19]
	v_mfma_f32_16x16x32_bf16 v[8:11], v[100:103], v[132:135], v[0:3]
	s_barrier
	s_add_i32 s55, s55, 2
	s_add_u32 s8, s8, 0x100
	s_addc_u32 s45, s45, 0
	s_add_u32 s6, s6, 0x100
	s_addc_u32 s7, s7, 0
	s_cmp_gt_u32 s55, 13
	s_cbranch_scc0 .LBB0_1291
	s_and_b64 vcc, exec, s[14:15]
	s_cbranch_vccz .LBB0_1294
	s_barrier

.LBB0_1518:
	s_add_u32 s23, s6, 0x100
	s_addc_u32 s60, s7, 0
	s_add_u32 s4, s4, 0x40080
	v_mov_b32_e32 v0, 0
	s_addc_u32 s5, s5, 0
	s_mov_b32 s61, -2
	ds_read_b128 v[128:131], v246
	ds_read_b128 v[132:135], v246 offset:1024
	ds_read_b128 v[136:139], v246 offset:2048
	ds_read_b128 v[140:143], v246 offset:3072
	ds_read_b128 v[144:147], v247
	ds_read_b128 v[148:151], v247 offset:1024
	ds_read_b128 v[152:155], v247 offset:2048
	ds_read_b128 v[156:159], v247 offset:3072
	s_add_u32 s6, s4, 0xfffc0080
	s_addc_u32 s7, s5, -1
	s_cmp_eq_u32 s61, 12
	s_cselect_b32 s35, s25, s7
	s_cselect_b32 s34, s24, s6
	s_cselect_b32 s7, s27, s60
	s_cselect_b32 s6, s26, s23
	v_lshl_add_u64 v[192:193], s[4:5], 0, v[218:219]
	s_add_i32 m0, s36, 0xc000
	ds_read_b128 v[160:163], v248
	ds_read_b128 v[164:167], v248 offset:1024
	ds_read_b128 v[168:171], v248 offset:2048
	ds_read_b128 v[172:175], v248 offset:3072
	ds_read_b128 v[176:179], v248 offset:4096
	ds_read_b128 v[180:183], v248 offset:5120
	ds_read_b128 v[184:187], v248 offset:6144
	ds_read_b128 v[188:191], v248 offset:7168
	global_load_lds_dwordx4 v[192:193], off
	v_lshl_add_u64 v[192:193], s[4:5], 0, v[216:217]
	s_add_i32 m0, s36, 0xe000
	s_nop 0
	global_load_lds_dwordx4 v[192:193], off
	s_waitcnt vmcnt(8)
	s_waitcnt lgkmcnt(0)
	s_barrier
	s_waitcnt lgkmcnt(0)
	v_mfma_f32_16x16x32_bf16 v[124:127], v[128:131], v[160:163], 0
	v_mfma_f32_16x16x32_bf16 v[120:123], v[136:139], v[160:163], 0
	v_mfma_f32_16x16x32_bf16 v[112:115], v[128:131], v[168:171], 0
	v_mfma_f32_16x16x32_bf16 v[104:107], v[136:139], v[168:171], 0
	v_mfma_f32_16x16x32_bf16 v[96:99], v[128:131], v[176:179], 0
	v_mfma_f32_16x16x32_bf16 v[88:91], v[136:139], v[176:179], 0
	v_mfma_f32_16x16x32_bf16 v[80:83], v[128:131], v[184:187], 0
	v_mfma_f32_16x16x32_bf16 v[72:75], v[136:139], v[184:187], 0
	v_mfma_f32_16x16x32_bf16 v[124:127], v[132:135], v[164:167], v[124:127]
	v_mfma_f32_16x16x32_bf16 v[120:123], v[140:143], v[164:167], v[120:123]
	v_mfma_f32_16x16x32_bf16 v[112:115], v[132:135], v[172:175], v[112:115]
	v_mfma_f32_16x16x32_bf16 v[104:107], v[140:143], v[172:175], v[104:107]
	v_mfma_f32_16x16x32_bf16 v[96:99], v[132:135], v[180:183], v[96:99]
	v_mfma_f32_16x16x32_bf16 v[88:91], v[140:143], v[180:183], v[88:91]
	v_mfma_f32_16x16x32_bf16 v[80:83], v[132:135], v[188:191], v[80:83]
	v_mfma_f32_16x16x32_bf16 v[72:75], v[140:143], v[188:191], v[72:75]
	v_mfma_f32_16x16x32_bf16 v[116:119], v[144:147], v[160:163], 0
	v_mfma_f32_16x16x32_bf16 v[108:111], v[152:155], v[160:163], 0
	v_mfma_f32_16x16x32_bf16 v[100:103], v[144:147], v[168:171], 0
	v_mfma_f32_16x16x32_bf16 v[92:95], v[152:155], v[168:171], 0
	v_mfma_f32_16x16x32_bf16 v[84:87], v[144:147], v[176:179], 0
	v_mfma_f32_16x16x32_bf16 v[76:79], v[152:155], v[176:179], 0
	v_mfma_f32_16x16x32_bf16 v[68:71], v[144:147], v[184:187], 0
	v_mfma_f32_16x16x32_bf16 v[64:67], v[152:155], v[184:187], 0
	v_mfma_f32_16x16x32_bf16 v[116:119], v[148:151], v[164:167], v[116:119]
	v_mfma_f32_16x16x32_bf16 v[108:111], v[156:159], v[164:167], v[108:111]
	v_mfma_f32_16x16x32_bf16 v[100:103], v[148:151], v[172:175], v[100:103]
	v_mfma_f32_16x16x32_bf16 v[92:95], v[156:159], v[172:175], v[92:95]
	v_mfma_f32_16x16x32_bf16 v[84:87], v[148:151], v[180:183], v[84:87]
	v_mfma_f32_16x16x32_bf16 v[76:79], v[156:159], v[180:183], v[76:79]
	v_mfma_f32_16x16x32_bf16 v[68:71], v[148:151], v[188:191], v[68:71]
	v_mfma_f32_16x16x32_bf16 v[64:67], v[156:159], v[188:191], v[64:67]
	s_barrier
	s_add_i32 s62, s48, s3
	v_lshl_add_u64 v[192:193], s[6:7], 0, v[212:213]
	s_mov_b32 m0, s62
	ds_read_b128 v[160:163], v248 offset:16384
	ds_read_b128 v[164:167], v248 offset:17408
	ds_read_b128 v[168:171], v248 offset:18432
	ds_read_b128 v[172:175], v248 offset:19456
	ds_read_b128 v[176:179], v248 offset:20480
	ds_read_b128 v[180:183], v248 offset:21504
	ds_read_b128 v[184:187], v248 offset:22528
	ds_read_b128 v[188:191], v248 offset:23552
	global_load_lds_dwordx4 v[192:193], off
	s_add_i32 m0, s62, 0x2000
	s_add_u32 s62, s6, 0x40000
	v_lshl_add_u64 v[194:195], s[6:7], 0, v[208:209]
	s_addc_u32 s63, s7, 0
	s_add_i32 s64, s49, s3
	global_load_lds_dwordx4 v[194:195], off
	v_lshl_add_u64 v[196:197], s[62:63], 0, v[212:213]
	s_mov_b32 m0, s64
	v_lshl_add_u64 v[198:199], s[34:35], 0, v[210:211]
	global_load_lds_dwordx4 v[196:197], off
	v_lshl_add_u64 v[196:197], s[62:63], 0, v[208:209]
	s_add_i32 m0, s64, 0x2000
	s_nop 0
	global_load_lds_dwordx4 v[196:197], off
	v_lshl_add_u64 v[196:197], s[34:35], 0, v[214:215]
	s_mov_b32 m0, s36
	s_nop 0
	global_load_lds_dwordx4 v[196:197], off
	s_mov_b32 m0, s37
	s_nop 0
	global_load_lds_dwordx4 v[198:199], off
	s_waitcnt vmcnt(8)
	s_waitcnt lgkmcnt(0)
	s_barrier
	s_waitcnt lgkmcnt(0)
	v_mfma_f32_16x16x32_bf16 v[60:63], v[128:131], v[160:163], 0
	v_mfma_f32_16x16x32_bf16 v[56:59], v[136:139], v[160:163], 0
	v_mfma_f32_16x16x32_bf16 v[48:51], v[128:131], v[168:171], 0
	v_mfma_f32_16x16x32_bf16 v[40:43], v[136:139], v[168:171], 0
	v_mfma_f32_16x16x32_bf16 v[32:35], v[128:131], v[176:179], 0
	v_mfma_f32_16x16x32_bf16 v[24:27], v[136:139], v[176:179], 0
	v_mfma_f32_16x16x32_bf16 v[16:19], v[128:131], v[184:187], 0
	v_mfma_f32_16x16x32_bf16 v[8:11], v[136:139], v[184:187], 0
	v_mfma_f32_16x16x32_bf16 v[60:63], v[132:135], v[164:167], v[60:63]
	v_mfma_f32_16x16x32_bf16 v[56:59], v[140:143], v[164:167], v[56:59]
	v_mfma_f32_16x16x32_bf16 v[48:51], v[132:135], v[172:175], v[48:51]
	v_mfma_f32_16x16x32_bf16 v[40:43], v[140:143], v[172:175], v[40:43]
	v_mfma_f32_16x16x32_bf16 v[32:35], v[132:135], v[180:183], v[32:35]
	v_mfma_f32_16x16x32_bf16 v[24:27], v[140:143], v[180:183], v[24:27]
	v_mfma_f32_16x16x32_bf16 v[16:19], v[132:135], v[188:191], v[16:19]
	v_mfma_f32_16x16x32_bf16 v[8:11], v[140:143], v[188:191], v[8:11]
	v_mfma_f32_16x16x32_bf16 v[52:55], v[144:147], v[160:163], 0
	v_mfma_f32_16x16x32_bf16 v[44:47], v[152:155], v[160:163], 0
	v_mfma_f32_16x16x32_bf16 v[36:39], v[144:147], v[168:171], 0
	v_mfma_f32_16x16x32_bf16 v[28:31], v[152:155], v[168:171], 0
	v_mfma_f32_16x16x32_bf16 v[20:23], v[144:147], v[176:179], 0
	v_mfma_f32_16x16x32_bf16 v[12:15], v[152:155], v[176:179], 0
	v_mfma_f32_16x16x32_bf16 v[4:7], v[144:147], v[184:187], 0
	v_mfma_f32_16x16x32_bf16 v[0:3], v[152:155], v[184:187], 0
	v_mfma_f32_16x16x32_bf16 v[52:55], v[148:151], v[164:167], v[52:55]
	v_mfma_f32_16x16x32_bf16 v[44:47], v[156:159], v[164:167], v[44:47]
	v_mfma_f32_16x16x32_bf16 v[36:39], v[148:151], v[172:175], v[36:39]
	v_mfma_f32_16x16x32_bf16 v[28:31], v[156:159], v[172:175], v[28:31]
	v_mfma_f32_16x16x32_bf16 v[20:23], v[148:151], v[180:183], v[20:23]
	v_mfma_f32_16x16x32_bf16 v[12:15], v[156:159], v[180:183], v[12:15]
	v_mfma_f32_16x16x32_bf16 v[4:7], v[148:151], v[188:191], v[4:7]
	v_mfma_f32_16x16x32_bf16 v[0:3], v[156:159], v[188:191], v[0:3]
	s_barrier
	s_add_i32 s62, 0, 0x18000
	s_add_i32 s63, 0, 0x1c000
	v_add_u32_e32 v140, s62, v245
	v_add_u32_e32 v156, s63, v245
	ds_read_b128 v[128:131], v140
	ds_read_b128 v[132:135], v140 offset:1024
	ds_read_b128 v[136:139], v140 offset:2048
	ds_read_b128 v[140:143], v140 offset:3072
	ds_read_b128 v[144:147], v156
	ds_read_b128 v[148:151], v156 offset:1024
	ds_read_b128 v[152:155], v156 offset:2048
	ds_read_b128 v[156:159], v156 offset:3072
	s_add_u32 s34, s34, 0x40000
	s_addc_u32 s35, s35, 0
	s_mov_b32 m0, s38
	v_lshl_add_u64 v[200:201], s[34:35], 0, v[214:215]
	ds_read_b128 v[160:163], v248 offset:32768
	ds_read_b128 v[164:167], v248 offset:33792
	ds_read_b128 v[168:171], v248 offset:34816
	ds_read_b128 v[172:175], v248 offset:35840
	ds_read_b128 v[176:179], v248 offset:36864
	ds_read_b128 v[180:183], v248 offset:37888
	ds_read_b128 v[184:187], v248 offset:38912
	ds_read_b128 v[188:191], v248 offset:39936
	global_load_lds_dwordx4 v[200:201], off
	v_lshl_add_u64 v[200:201], s[34:35], 0, v[210:211]
	s_mov_b32 m0, s39
	s_nop 0
	global_load_lds_dwordx4 v[200:201], off
	s_waitcnt vmcnt(8)
	s_waitcnt lgkmcnt(0)
	s_barrier
	s_waitcnt lgkmcnt(0)
	v_mfma_f32_16x16x32_bf16 v[124:127], v[128:131], v[160:163], v[124:127]
	v_mfma_f32_16x16x32_bf16 v[120:123], v[136:139], v[160:163], v[120:123]
	v_mfma_f32_16x16x32_bf16 v[112:115], v[128:131], v[168:171], v[112:115]
	v_mfma_f32_16x16x32_bf16 v[104:107], v[136:139], v[168:171], v[104:107]
	v_mfma_f32_16x16x32_bf16 v[96:99], v[128:131], v[176:179], v[96:99]
	v_mfma_f32_16x16x32_bf16 v[88:91], v[136:139], v[176:179], v[88:91]
	v_mfma_f32_16x16x32_bf16 v[80:83], v[128:131], v[184:187], v[80:83]
	v_mfma_f32_16x16x32_bf16 v[72:75], v[136:139], v[184:187], v[72:75]
	v_mfma_f32_16x16x32_bf16 v[124:127], v[132:135], v[164:167], v[124:127]
	v_mfma_f32_16x16x32_bf16 v[120:123], v[140:143], v[164:167], v[120:123]
	v_mfma_f32_16x16x32_bf16 v[112:115], v[132:135], v[172:175], v[112:115]
	v_mfma_f32_16x16x32_bf16 v[104:107], v[140:143], v[172:175], v[104:107]
	v_mfma_f32_16x16x32_bf16 v[96:99], v[132:135], v[180:183], v[96:99]
	v_mfma_f32_16x16x32_bf16 v[88:91], v[140:143], v[180:183], v[88:91]
	v_mfma_f32_16x16x32_bf16 v[80:83], v[132:135], v[188:191], v[80:83]
	v_mfma_f32_16x16x32_bf16 v[72:75], v[140:143], v[188:191], v[72:75]
	v_mfma_f32_16x16x32_bf16 v[116:119], v[144:147], v[160:163], v[116:119]
	v_mfma_f32_16x16x32_bf16 v[108:111], v[152:155], v[160:163], v[108:111]
	v_mfma_f32_16x16x32_bf16 v[100:103], v[144:147], v[168:171], v[100:103]
	v_mfma_f32_16x16x32_bf16 v[92:95], v[152:155], v[168:171], v[92:95]
	v_mfma_f32_16x16x32_bf16 v[84:87], v[144:147], v[176:179], v[84:87]
	v_mfma_f32_16x16x32_bf16 v[76:79], v[152:155], v[176:179], v[76:79]
	v_mfma_f32_16x16x32_bf16 v[68:71], v[144:147], v[184:187], v[68:71]
	v_mfma_f32_16x16x32_bf16 v[64:67], v[152:155], v[184:187], v[64:67]
	v_mfma_f32_16x16x32_bf16 v[116:119], v[148:151], v[164:167], v[116:119]
	v_mfma_f32_16x16x32_bf16 v[108:111], v[156:159], v[164:167], v[108:111]
	v_mfma_f32_16x16x32_bf16 v[100:103], v[148:151], v[172:175], v[100:103]
	v_mfma_f32_16x16x32_bf16 v[92:95], v[156:159], v[172:175], v[92:95]
	v_mfma_f32_16x16x32_bf16 v[84:87], v[148:151], v[180:183], v[84:87]
	v_mfma_f32_16x16x32_bf16 v[76:79], v[156:159], v[180:183], v[76:79]
	v_mfma_f32_16x16x32_bf16 v[68:71], v[148:151], v[188:191], v[68:71]
	v_mfma_f32_16x16x32_bf16 v[64:67], v[156:159], v[188:191], v[64:67]
	s_barrier
	s_add_i32 s34, s62, s3
	v_lshl_add_u64 v[192:193], v[192:193], 0, s[10:11]
	s_mov_b32 m0, s34
	ds_read_b128 v[160:163], v248 offset:49152
	ds_read_b128 v[164:167], v248 offset:50176
	ds_read_b128 v[168:171], v248 offset:51200
	ds_read_b128 v[172:175], v248 offset:52224
	ds_read_b128 v[176:179], v248 offset:53248
	ds_read_b128 v[180:183], v248 offset:54272
	ds_read_b128 v[184:187], v248 offset:55296
	ds_read_b128 v[188:191], v248 offset:56320
	global_load_lds_dwordx4 v[192:193], off
	s_add_i32 m0, s34, 0x2000
	s_add_u32 s6, s6, 0x40080
	v_lshl_add_u64 v[192:193], v[194:195], 0, s[10:11]
	s_addc_u32 s7, s7, 0
	s_add_i32 s34, s63, s3
	global_load_lds_dwordx4 v[192:193], off
	v_lshl_add_u64 v[192:193], s[6:7], 0, v[212:213]
	s_mov_b32 m0, s34
	s_nop 0
	global_load_lds_dwordx4 v[192:193], off
	v_lshl_add_u64 v[192:193], s[6:7], 0, v[208:209]
	s_add_i32 m0, s34, 0x2000
	s_nop 0
	global_load_lds_dwordx4 v[192:193], off
	v_lshl_add_u64 v[192:193], v[196:197], 0, s[10:11]
	s_mov_b32 m0, s44
	s_nop 0
	global_load_lds_dwordx4 v[192:193], off
	v_lshl_add_u64 v[192:193], v[198:199], 0, s[10:11]
	s_mov_b32 m0, s45
	s_nop 0
	global_load_lds_dwordx4 v[192:193], off
	s_waitcnt vmcnt(8)
	s_waitcnt lgkmcnt(0)
	s_barrier
	s_waitcnt lgkmcnt(0)
	v_mfma_f32_16x16x32_bf16 v[60:63], v[128:131], v[160:163], v[60:63]
	v_mfma_f32_16x16x32_bf16 v[56:59], v[136:139], v[160:163], v[56:59]
	v_mfma_f32_16x16x32_bf16 v[48:51], v[128:131], v[168:171], v[48:51]
	v_mfma_f32_16x16x32_bf16 v[40:43], v[136:139], v[168:171], v[40:43]
	v_mfma_f32_16x16x32_bf16 v[32:35], v[128:131], v[176:179], v[32:35]
	v_mfma_f32_16x16x32_bf16 v[24:27], v[136:139], v[176:179], v[24:27]
	v_mfma_f32_16x16x32_bf16 v[16:19], v[128:131], v[184:187], v[16:19]
	v_mfma_f32_16x16x32_bf16 v[8:11], v[136:139], v[184:187], v[8:11]
	v_mfma_f32_16x16x32_bf16 v[60:63], v[132:135], v[164:167], v[60:63]
	v_mfma_f32_16x16x32_bf16 v[56:59], v[140:143], v[164:167], v[56:59]
	v_mfma_f32_16x16x32_bf16 v[48:51], v[132:135], v[172:175], v[48:51]
	v_mfma_f32_16x16x32_bf16 v[40:43], v[140:143], v[172:175], v[40:43]
	v_mfma_f32_16x16x32_bf16 v[32:35], v[132:135], v[180:183], v[32:35]
	v_mfma_f32_16x16x32_bf16 v[24:27], v[140:143], v[180:183], v[24:27]
	v_mfma_f32_16x16x32_bf16 v[16:19], v[132:135], v[188:191], v[16:19]
	v_mfma_f32_16x16x32_bf16 v[8:11], v[140:143], v[188:191], v[8:11]
	v_mfma_f32_16x16x32_bf16 v[52:55], v[144:147], v[160:163], v[52:55]
	v_mfma_f32_16x16x32_bf16 v[44:47], v[152:155], v[160:163], v[44:47]
	v_mfma_f32_16x16x32_bf16 v[36:39], v[144:147], v[168:171], v[36:39]
	v_mfma_f32_16x16x32_bf16 v[28:31], v[152:155], v[168:171], v[28:31]
	v_mfma_f32_16x16x32_bf16 v[20:23], v[144:147], v[176:179], v[20:23]
	v_mfma_f32_16x16x32_bf16 v[12:15], v[152:155], v[176:179], v[12:15]
	v_mfma_f32_16x16x32_bf16 v[4:7], v[144:147], v[184:187], v[4:7]
	v_mfma_f32_16x16x32_bf16 v[0:3], v[152:155], v[184:187], v[0:3]
	v_mfma_f32_16x16x32_bf16 v[52:55], v[148:151], v[164:167], v[52:55]
	v_mfma_f32_16x16x32_bf16 v[44:47], v[156:159], v[164:167], v[44:47]
	v_mfma_f32_16x16x32_bf16 v[36:39], v[148:151], v[172:175], v[36:39]
	v_mfma_f32_16x16x32_bf16 v[28:31], v[156:159], v[172:175], v[28:31]
	v_mfma_f32_16x16x32_bf16 v[20:23], v[148:151], v[180:183], v[20:23]
	v_mfma_f32_16x16x32_bf16 v[12:15], v[156:159], v[180:183], v[12:15]
	v_mfma_f32_16x16x32_bf16 v[4:7], v[148:151], v[188:191], v[4:7]
	v_mfma_f32_16x16x32_bf16 v[0:3], v[156:159], v[188:191], v[0:3]
	s_barrier
	s_add_i32 s61, s61, 2
	s_add_u32 s23, s23, 0x100
	s_addc_u32 s60, s60, 0
	s_add_u32 s4, s4, 0x100
	s_addc_u32 s5, s5, 0
.LBB0_1519:
	ds_read_b128 v[128:131], v246
	ds_read_b128 v[132:135], v246 offset:1024
	ds_read_b128 v[136:139], v246 offset:2048
	ds_read_b128 v[140:143], v246 offset:3072
	ds_read_b128 v[144:147], v247
	ds_read_b128 v[148:151], v247 offset:1024
	ds_read_b128 v[152:155], v247 offset:2048
	ds_read_b128 v[156:159], v247 offset:3072
	s_add_u32 s6, s4, 0xfffc0080
	s_addc_u32 s7, s5, -1
	s_cmp_eq_u32 s61, 12
	s_cselect_b32 s35, s25, s7
	s_cselect_b32 s34, s24, s6
	s_cselect_b32 s7, s27, s60
	s_cselect_b32 s6, s26, s23
	v_lshl_add_u64 v[192:193], s[4:5], 0, v[218:219]
	s_add_i32 m0, s36, 0xc000
	ds_read_b128 v[160:163], v248
	ds_read_b128 v[164:167], v248 offset:1024
	ds_read_b128 v[168:171], v248 offset:2048
	ds_read_b128 v[172:175], v248 offset:3072
	ds_read_b128 v[176:179], v248 offset:4096
	ds_read_b128 v[180:183], v248 offset:5120
	ds_read_b128 v[184:187], v248 offset:6144
	ds_read_b128 v[188:191], v248 offset:7168
	global_load_lds_dwordx4 v[192:193], off
	v_lshl_add_u64 v[192:193], s[4:5], 0, v[216:217]
	s_add_i32 m0, s36, 0xe000
	s_nop 0
	global_load_lds_dwordx4 v[192:193], off
	s_waitcnt vmcnt(8)
	s_waitcnt lgkmcnt(0)
	s_barrier
	s_waitcnt lgkmcnt(0)
	v_mfma_f32_16x16x32_bf16 v[124:127], v[128:131], v[160:163], v[124:127]
	v_mfma_f32_16x16x32_bf16 v[120:123], v[136:139], v[160:163], v[120:123]
	v_mfma_f32_16x16x32_bf16 v[112:115], v[128:131], v[168:171], v[112:115]
	v_mfma_f32_16x16x32_bf16 v[104:107], v[136:139], v[168:171], v[104:107]
	v_mfma_f32_16x16x32_bf16 v[96:99], v[128:131], v[176:179], v[96:99]
	v_mfma_f32_16x16x32_bf16 v[88:91], v[136:139], v[176:179], v[88:91]
	v_mfma_f32_16x16x32_bf16 v[80:83], v[128:131], v[184:187], v[80:83]
	v_mfma_f32_16x16x32_bf16 v[72:75], v[136:139], v[184:187], v[72:75]
	v_mfma_f32_16x16x32_bf16 v[124:127], v[132:135], v[164:167], v[124:127]
	v_mfma_f32_16x16x32_bf16 v[120:123], v[140:143], v[164:167], v[120:123]
	v_mfma_f32_16x16x32_bf16 v[112:115], v[132:135], v[172:175], v[112:115]
	v_mfma_f32_16x16x32_bf16 v[104:107], v[140:143], v[172:175], v[104:107]
	v_mfma_f32_16x16x32_bf16 v[96:99], v[132:135], v[180:183], v[96:99]
	v_mfma_f32_16x16x32_bf16 v[88:91], v[140:143], v[180:183], v[88:91]
	v_mfma_f32_16x16x32_bf16 v[80:83], v[132:135], v[188:191], v[80:83]
	v_mfma_f32_16x16x32_bf16 v[72:75], v[140:143], v[188:191], v[72:75]
	v_mfma_f32_16x16x32_bf16 v[116:119], v[144:147], v[160:163], v[116:119]
	v_mfma_f32_16x16x32_bf16 v[108:111], v[152:155], v[160:163], v[108:111]
	v_mfma_f32_16x16x32_bf16 v[100:103], v[144:147], v[168:171], v[100:103]
	v_mfma_f32_16x16x32_bf16 v[92:95], v[152:155], v[168:171], v[92:95]
	v_mfma_f32_16x16x32_bf16 v[84:87], v[144:147], v[176:179], v[84:87]
	v_mfma_f32_16x16x32_bf16 v[76:79], v[152:155], v[176:179], v[76:79]
	v_mfma_f32_16x16x32_bf16 v[68:71], v[144:147], v[184:187], v[68:71]
	v_mfma_f32_16x16x32_bf16 v[64:67], v[152:155], v[184:187], v[64:67]
	v_mfma_f32_16x16x32_bf16 v[116:119], v[148:151], v[164:167], v[116:119]
	v_mfma_f32_16x16x32_bf16 v[108:111], v[156:159], v[164:167], v[108:111]
	v_mfma_f32_16x16x32_bf16 v[100:103], v[148:151], v[172:175], v[100:103]
	v_mfma_f32_16x16x32_bf16 v[92:95], v[156:159], v[172:175], v[92:95]
	v_mfma_f32_16x16x32_bf16 v[84:87], v[148:151], v[180:183], v[84:87]
	v_mfma_f32_16x16x32_bf16 v[76:79], v[156:159], v[180:183], v[76:79]
	v_mfma_f32_16x16x32_bf16 v[68:71], v[148:151], v[188:191], v[68:71]
	v_mfma_f32_16x16x32_bf16 v[64:67], v[156:159], v[188:191], v[64:67]
	s_barrier
	s_add_i32 s62, s48, s3
	v_lshl_add_u64 v[192:193], s[6:7], 0, v[212:213]
	s_mov_b32 m0, s62
	ds_read_b128 v[160:163], v248 offset:16384
	ds_read_b128 v[164:167], v248 offset:17408
	ds_read_b128 v[168:171], v248 offset:18432
	ds_read_b128 v[172:175], v248 offset:19456
	ds_read_b128 v[176:179], v248 offset:20480
	ds_read_b128 v[180:183], v248 offset:21504
	ds_read_b128 v[184:187], v248 offset:22528
	ds_read_b128 v[188:191], v248 offset:23552
	global_load_lds_dwordx4 v[192:193], off
	s_add_i32 m0, s62, 0x2000
	s_add_u32 s62, s6, 0x40000
	v_lshl_add_u64 v[194:195], s[6:7], 0, v[208:209]
	s_addc_u32 s63, s7, 0
	s_add_i32 s64, s49, s3
	global_load_lds_dwordx4 v[194:195], off
	v_lshl_add_u64 v[196:197], s[62:63], 0, v[212:213]
	s_mov_b32 m0, s64
	v_lshl_add_u64 v[198:199], s[34:35], 0, v[210:211]
	global_load_lds_dwordx4 v[196:197], off
	v_lshl_add_u64 v[196:197], s[62:63], 0, v[208:209]
	s_add_i32 m0, s64, 0x2000
	s_nop 0
	global_load_lds_dwordx4 v[196:197], off
	v_lshl_add_u64 v[196:197], s[34:35], 0, v[214:215]
	s_mov_b32 m0, s36
	s_nop 0
	global_load_lds_dwordx4 v[196:197], off
	s_mov_b32 m0, s37
	s_nop 0
	global_load_lds_dwordx4 v[198:199], off
	s_waitcnt vmcnt(8)
	s_waitcnt lgkmcnt(0)
	s_barrier
	s_waitcnt lgkmcnt(0)
	v_mfma_f32_16x16x32_bf16 v[60:63], v[128:131], v[160:163], v[60:63]
	v_mfma_f32_16x16x32_bf16 v[56:59], v[136:139], v[160:163], v[56:59]
	v_mfma_f32_16x16x32_bf16 v[48:51], v[128:131], v[168:171], v[48:51]
	v_mfma_f32_16x16x32_bf16 v[40:43], v[136:139], v[168:171], v[40:43]
	v_mfma_f32_16x16x32_bf16 v[32:35], v[128:131], v[176:179], v[32:35]
	v_mfma_f32_16x16x32_bf16 v[24:27], v[136:139], v[176:179], v[24:27]
	v_mfma_f32_16x16x32_bf16 v[16:19], v[128:131], v[184:187], v[16:19]
	v_mfma_f32_16x16x32_bf16 v[8:11], v[136:139], v[184:187], v[8:11]
	v_mfma_f32_16x16x32_bf16 v[60:63], v[132:135], v[164:167], v[60:63]
	v_mfma_f32_16x16x32_bf16 v[56:59], v[140:143], v[164:167], v[56:59]
	v_mfma_f32_16x16x32_bf16 v[48:51], v[132:135], v[172:175], v[48:51]
	v_mfma_f32_16x16x32_bf16 v[40:43], v[140:143], v[172:175], v[40:43]
	v_mfma_f32_16x16x32_bf16 v[32:35], v[132:135], v[180:183], v[32:35]
	v_mfma_f32_16x16x32_bf16 v[24:27], v[140:143], v[180:183], v[24:27]
	v_mfma_f32_16x16x32_bf16 v[16:19], v[132:135], v[188:191], v[16:19]
	v_mfma_f32_16x16x32_bf16 v[8:11], v[140:143], v[188:191], v[8:11]
	v_mfma_f32_16x16x32_bf16 v[52:55], v[144:147], v[160:163], v[52:55]
	v_mfma_f32_16x16x32_bf16 v[44:47], v[152:155], v[160:163], v[44:47]
	v_mfma_f32_16x16x32_bf16 v[36:39], v[144:147], v[168:171], v[36:39]
	v_mfma_f32_16x16x32_bf16 v[28:31], v[152:155], v[168:171], v[28:31]
	v_mfma_f32_16x16x32_bf16 v[20:23], v[144:147], v[176:179], v[20:23]
	v_mfma_f32_16x16x32_bf16 v[12:15], v[152:155], v[176:179], v[12:15]
	v_mfma_f32_16x16x32_bf16 v[4:7], v[144:147], v[184:187], v[4:7]
	v_mfma_f32_16x16x32_bf16 v[0:3], v[152:155], v[184:187], v[0:3]
	v_mfma_f32_16x16x32_bf16 v[52:55], v[148:151], v[164:167], v[52:55]
	v_mfma_f32_16x16x32_bf16 v[44:47], v[156:159], v[164:167], v[44:47]
	v_mfma_f32_16x16x32_bf16 v[36:39], v[148:151], v[172:175], v[36:39]
	v_mfma_f32_16x16x32_bf16 v[28:31], v[156:159], v[172:175], v[28:31]
	v_mfma_f32_16x16x32_bf16 v[20:23], v[148:151], v[180:183], v[20:23]
	v_mfma_f32_16x16x32_bf16 v[12:15], v[156:159], v[180:183], v[12:15]
	v_mfma_f32_16x16x32_bf16 v[4:7], v[148:151], v[188:191], v[4:7]
	v_mfma_f32_16x16x32_bf16 v[0:3], v[156:159], v[188:191], v[0:3]
	s_barrier
	s_add_i32 s62, 0, 0x18000
	s_add_i32 s63, 0, 0x1c000
	v_add_u32_e32 v140, s62, v245
	v_add_u32_e32 v156, s63, v245
	ds_read_b128 v[128:131], v140
	ds_read_b128 v[132:135], v140 offset:1024
	ds_read_b128 v[136:139], v140 offset:2048
	ds_read_b128 v[140:143], v140 offset:3072
	ds_read_b128 v[144:147], v156
	ds_read_b128 v[148:151], v156 offset:1024
	ds_read_b128 v[152:155], v156 offset:2048
	ds_read_b128 v[156:159], v156 offset:3072
	s_add_u32 s34, s34, 0x40000
	s_addc_u32 s35, s35, 0
	s_mov_b32 m0, s38
	v_lshl_add_u64 v[200:201], s[34:35], 0, v[214:215]
	ds_read_b128 v[160:163], v248 offset:32768
	ds_read_b128 v[164:167], v248 offset:33792
	ds_read_b128 v[168:171], v248 offset:34816
	ds_read_b128 v[172:175], v248 offset:35840
	ds_read_b128 v[176:179], v248 offset:36864
	ds_read_b128 v[180:183], v248 offset:37888
	ds_read_b128 v[184:187], v248 offset:38912
	ds_read_b128 v[188:191], v248 offset:39936
	global_load_lds_dwordx4 v[200:201], off
	v_lshl_add_u64 v[200:201], s[34:35], 0, v[210:211]
	s_mov_b32 m0, s39
	s_nop 0
	global_load_lds_dwordx4 v[200:201], off
	s_waitcnt vmcnt(8)
	s_waitcnt lgkmcnt(0)
	s_barrier
	s_waitcnt lgkmcnt(0)
	v_mfma_f32_16x16x32_bf16 v[124:127], v[128:131], v[160:163], v[124:127]
	v_mfma_f32_16x16x32_bf16 v[120:123], v[136:139], v[160:163], v[120:123]
	v_mfma_f32_16x16x32_bf16 v[112:115], v[128:131], v[168:171], v[112:115]
	v_mfma_f32_16x16x32_bf16 v[104:107], v[136:139], v[168:171], v[104:107]
	v_mfma_f32_16x16x32_bf16 v[96:99], v[128:131], v[176:179], v[96:99]
	v_mfma_f32_16x16x32_bf16 v[88:91], v[136:139], v[176:179], v[88:91]
	v_mfma_f32_16x16x32_bf16 v[80:83], v[128:131], v[184:187], v[80:83]
	v_mfma_f32_16x16x32_bf16 v[72:75], v[136:139], v[184:187], v[72:75]
	v_mfma_f32_16x16x32_bf16 v[124:127], v[132:135], v[164:167], v[124:127]
	v_mfma_f32_16x16x32_bf16 v[120:123], v[140:143], v[164:167], v[120:123]
	v_mfma_f32_16x16x32_bf16 v[112:115], v[132:135], v[172:175], v[112:115]
	v_mfma_f32_16x16x32_bf16 v[104:107], v[140:143], v[172:175], v[104:107]
	v_mfma_f32_16x16x32_bf16 v[96:99], v[132:135], v[180:183], v[96:99]
	v_mfma_f32_16x16x32_bf16 v[88:91], v[140:143], v[180:183], v[88:91]
	v_mfma_f32_16x16x32_bf16 v[80:83], v[132:135], v[188:191], v[80:83]
	v_mfma_f32_16x16x32_bf16 v[72:75], v[140:143], v[188:191], v[72:75]
	v_mfma_f32_16x16x32_bf16 v[116:119], v[144:147], v[160:163], v[116:119]
	v_mfma_f32_16x16x32_bf16 v[108:111], v[152:155], v[160:163], v[108:111]
	v_mfma_f32_16x16x32_bf16 v[100:103], v[144:147], v[168:171], v[100:103]
	v_mfma_f32_16x16x32_bf16 v[92:95], v[152:155], v[168:171], v[92:95]
	v_mfma_f32_16x16x32_bf16 v[84:87], v[144:147], v[176:179], v[84:87]
	v_mfma_f32_16x16x32_bf16 v[76:79], v[152:155], v[176:179], v[76:79]
	v_mfma_f32_16x16x32_bf16 v[68:71], v[144:147], v[184:187], v[68:71]
	v_mfma_f32_16x16x32_bf16 v[64:67], v[152:155], v[184:187], v[64:67]
	v_mfma_f32_16x16x32_bf16 v[116:119], v[148:151], v[164:167], v[116:119]
	v_mfma_f32_16x16x32_bf16 v[108:111], v[156:159], v[164:167], v[108:111]
	v_mfma_f32_16x16x32_bf16 v[100:103], v[148:151], v[172:175], v[100:103]
	v_mfma_f32_16x16x32_bf16 v[92:95], v[156:159], v[172:175], v[92:95]
	v_mfma_f32_16x16x32_bf16 v[84:87], v[148:151], v[180:183], v[84:87]
	v_mfma_f32_16x16x32_bf16 v[76:79], v[156:159], v[180:183], v[76:79]
	v_mfma_f32_16x16x32_bf16 v[68:71], v[148:151], v[188:191], v[68:71]
	v_mfma_f32_16x16x32_bf16 v[64:67], v[156:159], v[188:191], v[64:67]
	s_barrier
	s_add_i32 s34, s62, s3
	v_lshl_add_u64 v[192:193], v[192:193], 0, s[10:11]
	s_mov_b32 m0, s34
	ds_read_b128 v[160:163], v248 offset:49152
	ds_read_b128 v[164:167], v248 offset:50176
	ds_read_b128 v[168:171], v248 offset:51200
	ds_read_b128 v[172:175], v248 offset:52224
	ds_read_b128 v[176:179], v248 offset:53248
	ds_read_b128 v[180:183], v248 offset:54272
	ds_read_b128 v[184:187], v248 offset:55296
	ds_read_b128 v[188:191], v248 offset:56320
	global_load_lds_dwordx4 v[192:193], off
	s_add_i32 m0, s34, 0x2000
	s_add_u32 s6, s6, 0x40080
	v_lshl_add_u64 v[192:193], v[194:195], 0, s[10:11]
	s_addc_u32 s7, s7, 0
	s_add_i32 s34, s63, s3
	global_load_lds_dwordx4 v[192:193], off
	v_lshl_add_u64 v[192:193], s[6:7], 0, v[212:213]
	s_mov_b32 m0, s34
	s_nop 0
	global_load_lds_dwordx4 v[192:193], off
	v_lshl_add_u64 v[192:193], s[6:7], 0, v[208:209]
	s_add_i32 m0, s34, 0x2000
	s_nop 0
	global_load_lds_dwordx4 v[192:193], off
	v_lshl_add_u64 v[192:193], v[196:197], 0, s[10:11]
	s_mov_b32 m0, s44
	s_nop 0
	global_load_lds_dwordx4 v[192:193], off
	v_lshl_add_u64 v[192:193], v[198:199], 0, s[10:11]
	s_mov_b32 m0, s45
	s_nop 0
	global_load_lds_dwordx4 v[192:193], off
	s_waitcnt vmcnt(8)
	s_waitcnt lgkmcnt(0)
	s_barrier
	s_waitcnt lgkmcnt(0)
	v_mfma_f32_16x16x32_bf16 v[60:63], v[128:131], v[160:163], v[60:63]
	v_mfma_f32_16x16x32_bf16 v[56:59], v[136:139], v[160:163], v[56:59]
	v_mfma_f32_16x16x32_bf16 v[48:51], v[128:131], v[168:171], v[48:51]
	v_mfma_f32_16x16x32_bf16 v[40:43], v[136:139], v[168:171], v[40:43]
	v_mfma_f32_16x16x32_bf16 v[32:35], v[128:131], v[176:179], v[32:35]
	v_mfma_f32_16x16x32_bf16 v[24:27], v[136:139], v[176:179], v[24:27]
	v_mfma_f32_16x16x32_bf16 v[16:19], v[128:131], v[184:187], v[16:19]
	v_mfma_f32_16x16x32_bf16 v[8:11], v[136:139], v[184:187], v[8:11]
	v_mfma_f32_16x16x32_bf16 v[60:63], v[132:135], v[164:167], v[60:63]
	v_mfma_f32_16x16x32_bf16 v[56:59], v[140:143], v[164:167], v[56:59]
	v_mfma_f32_16x16x32_bf16 v[48:51], v[132:135], v[172:175], v[48:51]
	v_mfma_f32_16x16x32_bf16 v[40:43], v[140:143], v[172:175], v[40:43]
	v_mfma_f32_16x16x32_bf16 v[32:35], v[132:135], v[180:183], v[32:35]
	v_mfma_f32_16x16x32_bf16 v[24:27], v[140:143], v[180:183], v[24:27]
	v_mfma_f32_16x16x32_bf16 v[16:19], v[132:135], v[188:191], v[16:19]
	v_mfma_f32_16x16x32_bf16 v[8:11], v[140:143], v[188:191], v[8:11]
	v_mfma_f32_16x16x32_bf16 v[52:55], v[144:147], v[160:163], v[52:55]
	v_mfma_f32_16x16x32_bf16 v[44:47], v[152:155], v[160:163], v[44:47]
	v_mfma_f32_16x16x32_bf16 v[36:39], v[144:147], v[168:171], v[36:39]
	v_mfma_f32_16x16x32_bf16 v[28:31], v[152:155], v[168:171], v[28:31]
	v_mfma_f32_16x16x32_bf16 v[20:23], v[144:147], v[176:179], v[20:23]
	v_mfma_f32_16x16x32_bf16 v[12:15], v[152:155], v[176:179], v[12:15]
	v_mfma_f32_16x16x32_bf16 v[4:7], v[144:147], v[184:187], v[4:7]
	v_mfma_f32_16x16x32_bf16 v[0:3], v[152:155], v[184:187], v[0:3]
	v_mfma_f32_16x16x32_bf16 v[52:55], v[148:151], v[164:167], v[52:55]
	v_mfma_f32_16x16x32_bf16 v[44:47], v[156:159], v[164:167], v[44:47]
	v_mfma_f32_16x16x32_bf16 v[36:39], v[148:151], v[172:175], v[36:39]
	v_mfma_f32_16x16x32_bf16 v[28:31], v[156:159], v[172:175], v[28:31]
	v_mfma_f32_16x16x32_bf16 v[20:23], v[148:151], v[180:183], v[20:23]
	v_mfma_f32_16x16x32_bf16 v[12:15], v[156:159], v[180:183], v[12:15]
	v_mfma_f32_16x16x32_bf16 v[4:7], v[148:151], v[188:191], v[4:7]
	v_mfma_f32_16x16x32_bf16 v[0:3], v[156:159], v[188:191], v[0:3]
	s_barrier
	s_add_i32 s61, s61, 2
	s_add_u32 s23, s23, 0x100
	s_addc_u32 s60, s60, 0
	s_add_u32 s4, s4, 0x100
	s_addc_u32 s5, s5, 0
	s_cmp_gt_u32 s61, 13
	s_cbranch_scc0 .LBB0_1519
	s_and_b64 vcc, exec, s[12:13]
	s_cbranch_vccz .LBB0_1522
	s_barrier
